# sample_out_block partial-sum merge: the 32 LDS reads issued together instead of one per wait
# baseline (speedup 1.0000x reference)
; #define LAS __attribute__((address_space(3)))
; #define MFMA16(a, b, c) __builtin_amdgcn_mfma_f32_16x16x32_bf16((a), (b), (c), 0, 0, 0)
; __device__ __forceinline__ void sample_out_block(LAS unsigned char* lds, const bf16_t* A, const bf16_t* Bt, int K, bf16_t* xb, float* sspart, int blk, int tid) {
;     const int wave = tid >> 6, lane = tid & 63, l15 = lane & 15, g = lane >> 4;
;     const int rt = blk >> 5, cg = blk & 31, r0 = T_P + 32 * rt;
;     const int kq = K >> 3;
;     f32x4 acc[2][4];
; #pragma unroll
;     for (int ra = 0; ra < 2; ++ra)
; #pragma unroll
;         for (int nt = 0; nt < 4; ++nt) acc[ra][nt] = (f32x4){0.f, 0.f, 0.f, 0.f};
;     {
;         const bf16_t* ap = A + (size_t)(r0 + l15) * K + wave * kq + 8 * g;
;         const bf16_t* bp = Bt + (size_t)(64 * cg + l15) * K + wave * kq + 8 * g;
;         bf16x8 af[2][2], bf[2][4], afn[2][2], bfn[2][4];
; #pragma unroll
;         for (int s = 0; s < 2; ++s) {
; #pragma unroll
;             for (int ra = 0; ra < 2; ++ra) af[s][ra] = *(const bf16x8*)(ap + (size_t)(16 * ra) * K + 32 * s);
; #pragma unroll
;             for (int nt = 0; nt < 4; ++nt) bf[s][nt] = *(const bf16x8*)(bp + (size_t)(16 * nt) * K + 32 * s);
;         }
;         for (int k0 = 0; k0 < kq; k0 += 64) {
;             const int k1 = (k0 + 64 < kq) ? k0 + 64 : k0;
; #pragma unroll
;             for (int s = 0; s < 2; ++s) {
; #pragma unroll
;                 for (int ra = 0; ra < 2; ++ra) afn[s][ra] = *(const bf16x8*)(ap + (size_t)(16 * ra) * K + k1 + 32 * s);
; #pragma unroll
;                 for (int nt = 0; nt < 4; ++nt) bfn[s][nt] = *(const bf16x8*)(bp + (size_t)(16 * nt) * K + k1 + 32 * s);
;             }
; #pragma unroll
;             for (int s = 0; s < 2; ++s)
; #pragma unroll
;                 for (int ra = 0; ra < 2; ++ra)
; #pragma unroll
;                     for (int nt = 0; nt < 4; ++nt) acc[ra][nt] = MFMA16(af[s][ra], bf[s][nt], acc[ra][nt]);
.LBB0_542:
	s_and_b32 s27, s34, 0xffffffe0
	s_addk_i32 s27, 0x2000
	s_and_b32 s26, s34, 31
	v_or_b32_e32 v8, s27, v30
	v_ashrrev_i32_e32 v9, 31, v8
	s_lshl_b32 s35, s26, 6
	v_lshlrev_b64 v[8:9], 13, v[8:9]
	v_or_b32_e32 v0, s35, v30
	v_lshl_add_u64 v[10:11], v[2:3], 0, v[8:9]
	v_lshlrev_b32_e32 v0, 13, v0
	v_lshl_add_u64 v[16:17], v[4:5], 0, v[0:1]
	v_add_co_u32_e32 v8, vcc, 0x20000, v10
	s_mov_b64 s[10:11], vcc
	v_add_co_u32_e32 v12, vcc, 0x20000, v16
	v_readfirstlane_b32 s36, v139
	s_lshr_b32 s36, s36, 6
	s_and_b32 s37, s34, 0xffffffe0
	s_addk_i32 s37, 0x2000
	s_and_b32 s38, s34, 31
	s_lshl_b32 s38, s38, 6
	s_lshl_b32 s39, s37, 13
	s_mul_i32 s40, s36, 0x400
	s_add_u32 s42, s24, s39
	s_addc_u32 s43, s25, 0
	s_add_u32 s42, s42, s40
	s_addc_u32 s43, s43, 0
	s_lshl_b32 s41, s30, 1
	s_lshl_b32 s39, s38, 13
	s_add_u32 s44, s28, s41
	s_addc_u32 s45, s29, 0
	s_add_u32 s44, s44, s39
	s_addc_u32 s45, s45, 0
	s_add_u32 s44, s44, s40
	s_addc_u32 s45, s45, 0
	v_lshrrev_b32_e32 v227, 3, v215
	v_and_b32_e32 v228, 7, v215
	v_lshlrev_b32_e32 v198, 13, v227
	v_lshl_add_u32 v198, v228, 4, v198
	v_add_u32_e32 v199, 0x10000, v198
	v_add_u32_e32 v200, 0x20000, v198
	v_add_u32_e32 v201, 0x30000, v198
	v_add_u32_e32 v202, 0x40000, v198
	v_add_u32_e32 v203, 0x50000, v198
	v_add_u32_e32 v204, 0x60000, v198
	v_add_u32_e32 v205, 0x70000, v198
	s_lshl_b32 s46, s36, 13
	s_mul_i32 s47, s36, 0x1800
	s_add_i32 s47, s47, 0x10000
	v_mul_u32_u24_e32 v206, 0x90, v227
	v_lshl_add_u32 v206, v228, 4, v206
	v_add_u32_e32 v207, s47, v206
	v_add_u32_e32 v206, s46, v206
	v_and_b32_e32 v227, 15, v215
	v_lshrrev_b32_e32 v228, 4, v215
	v_mul_u32_u24_e32 v208, 0x90, v227
	v_lshl_add_u32 v208, v228, 4, v208
	v_add_u32_e32 v209, s47, v208
	v_add_u32_e32 v208, s46, v208
	v_add_u32_e32 v226, 0x1b00, v208
	v_subrev_u32_e32 v228, 0x480, v209
	v_cmp_gt_u32_e32 vcc, 8, v227
	v_cndmask_b32_e32 v226, v228, v226, vcc
	global_load_dwordx4 v[34:37], v198, s[42:43]
	global_load_dwordx4 v[38:41], v199, s[42:43]
	global_load_dwordx4 v[42:45], v200, s[42:43]
	global_load_dwordx4 v[46:49], v201, s[42:43]
	global_load_dwordx4 v[50:53], v198, s[44:45]
	global_load_dwordx4 v[54:57], v199, s[44:45]
	global_load_dwordx4 v[58:61], v200, s[44:45]
	global_load_dwordx4 v[62:65], v201, s[44:45]
	global_load_dwordx4 v[66:69], v202, s[44:45]
	global_load_dwordx4 v[70:73], v203, s[44:45]
	global_load_dwordx4 v[74:77], v204, s[44:45]
	global_load_dwordx4 v[78:81], v205, s[44:45]
	global_load_dwordx4 v[82:85], v198, s[42:43] offset:128
	global_load_dwordx4 v[86:89], v199, s[42:43] offset:128
	global_load_dwordx4 v[90:93], v200, s[42:43] offset:128
	global_load_dwordx4 v[94:97], v201, s[42:43] offset:128
	global_load_dwordx4 v[98:101], v198, s[44:45] offset:128
	global_load_dwordx4 v[102:105], v199, s[44:45] offset:128
	global_load_dwordx4 v[106:109], v200, s[44:45] offset:128
	global_load_dwordx4 v[110:113], v201, s[44:45] offset:128
	global_load_dwordx4 v[114:117], v202, s[44:45] offset:128
	global_load_dwordx4 v[118:121], v203, s[44:45] offset:128
	global_load_dwordx4 v[122:125], v204, s[44:45] offset:128
	global_load_dwordx4 v[126:129], v205, s[44:45] offset:128
	s_waitcnt vmcnt(12)
	ds_write_b128 v206, v[34:37]
	ds_write_b128 v206, v[38:41] offset:1152
	ds_write_b128 v206, v[42:45] offset:2304
	ds_write_b128 v206, v[46:49] offset:3456
	ds_write_b128 v206, v[50:53] offset:4608
	ds_write_b128 v206, v[54:57] offset:5760
	ds_write_b128 v206, v[58:61] offset:6912
	ds_write_b128 v207, v[62:65]
	ds_write_b128 v207, v[66:69] offset:1152
	ds_write_b128 v207, v[70:73] offset:2304
	ds_write_b128 v207, v[74:77] offset:3456
	ds_write_b128 v207, v[78:81] offset:4608
	global_load_dwordx4 v[34:37], v198, s[42:43] offset:256
	global_load_dwordx4 v[38:41], v199, s[42:43] offset:256
	global_load_dwordx4 v[42:45], v200, s[42:43] offset:256
	global_load_dwordx4 v[46:49], v201, s[42:43] offset:256
	global_load_dwordx4 v[50:53], v198, s[44:45] offset:256
	global_load_dwordx4 v[54:57], v199, s[44:45] offset:256
	global_load_dwordx4 v[58:61], v200, s[44:45] offset:256
	global_load_dwordx4 v[62:65], v201, s[44:45] offset:256
	global_load_dwordx4 v[66:69], v202, s[44:45] offset:256
	global_load_dwordx4 v[70:73], v203, s[44:45] offset:256
	global_load_dwordx4 v[74:77], v204, s[44:45] offset:256
	global_load_dwordx4 v[78:81], v205, s[44:45] offset:256
	ds_read_b128 v[146:149], v208 offset:0
	ds_read_b128 v[150:153], v208 offset:2304
	ds_read_b128 v[154:157], v208 offset:4608
	ds_read_b128 v[158:161], v226
	ds_read_b128 v[162:165], v209 offset:1152
	ds_read_b128 v[166:169], v209 offset:3456
	ds_read_b128 v[170:173], v208 offset:64
	ds_read_b128 v[174:177], v208 offset:2368
	ds_read_b128 v[178:181], v208 offset:4672
	ds_read_b128 v[182:185], v226 offset:64
	ds_read_b128 v[186:189], v209 offset:1216
	ds_read_b128 v[190:193], v209 offset:3520
	s_waitcnt lgkmcnt(6)
	v_mfma_f32_16x16x32_bf16 v[8:11], v[146:149], v[154:157], 0
	v_mfma_f32_16x16x32_bf16 v[12:15], v[146:149], v[158:161], 0
	v_mfma_f32_16x16x32_bf16 v[16:19], v[146:149], v[162:165], 0
	v_mfma_f32_16x16x32_bf16 v[20:23], v[146:149], v[166:169], 0
	v_mfma_f32_16x16x32_bf16 v[24:27], v[150:153], v[154:157], 0
	v_mfma_f32_16x16x32_bf16 v[130:133], v[150:153], v[158:161], 0
	v_mfma_f32_16x16x32_bf16 v[134:137], v[150:153], v[162:165], 0
	v_mfma_f32_16x16x32_bf16 v[194:197], v[150:153], v[166:169], 0
	s_waitcnt lgkmcnt(0)
; #define MFMA16(a, b, c) __builtin_amdgcn_mfma_f32_16x16x32_bf16((a), (b), (c), 0, 0, 0)
; __device__ __forceinline__ void sample_out_block(LAS unsigned char* lds, const bf16_t* A, const bf16_t* Bt, int K, bf16_t* xb, float* sspart, int blk, int tid) {
;     ...
;         for (int k0 = 0; k0 < kq; k0 += 64) {
;             const int k1 = (k0 + 64 < kq) ? k0 + 64 : k0;
; #pragma unroll
;             for (int s = 0; s < 2; ++s) {
; #pragma unroll
;                 for (int ra = 0; ra < 2; ++ra) afn[s][ra] = *(const bf16x8*)(ap + (size_t)(16 * ra) * K + k1 + 32 * s);
; #pragma unroll
;                 for (int nt = 0; nt < 4; ++nt) bfn[s][nt] = *(const bf16x8*)(bp + (size_t)(16 * nt) * K + k1 + 32 * s);
;             }
; #pragma unroll
;             for (int s = 0; s < 2; ++s)
; #pragma unroll
;                 for (int ra = 0; ra < 2; ++ra)
; #pragma unroll
;                     for (int nt = 0; nt < 4; ++nt) acc[ra][nt] = MFMA16(af[s][ra], bf[s][nt], acc[ra][nt]);
; #pragma unroll
;             for (int s = 0; s < 2; ++s) {
; #pragma unroll
;                 for (int ra = 0; ra < 2; ++ra) af[s][ra] = afn[s][ra];
; #pragma unroll
;                 for (int nt = 0; nt < 4; ++nt) bf[s][nt] = bfn[s][nt];
;             }
;         }
	v_mfma_f32_16x16x32_bf16 v[8:11], v[170:173], v[178:181], v[8:11]
	v_mfma_f32_16x16x32_bf16 v[12:15], v[170:173], v[182:185], v[12:15]
	v_mfma_f32_16x16x32_bf16 v[16:19], v[170:173], v[186:189], v[16:19]
	v_mfma_f32_16x16x32_bf16 v[20:23], v[170:173], v[190:193], v[20:23]
	v_mfma_f32_16x16x32_bf16 v[24:27], v[174:177], v[178:181], v[24:27]
	v_mfma_f32_16x16x32_bf16 v[130:133], v[174:177], v[182:185], v[130:133]
	v_mfma_f32_16x16x32_bf16 v[134:137], v[174:177], v[186:189], v[134:137]
	v_mfma_f32_16x16x32_bf16 v[194:197], v[174:177], v[190:193], v[194:197]
	s_waitcnt vmcnt(12)
	ds_write_b128 v206, v[82:85]
	ds_write_b128 v206, v[86:89] offset:1152
	ds_write_b128 v206, v[90:93] offset:2304
	ds_write_b128 v206, v[94:97] offset:3456
	ds_write_b128 v206, v[98:101] offset:4608
	ds_write_b128 v206, v[102:105] offset:5760
	ds_write_b128 v206, v[106:109] offset:6912
	ds_write_b128 v207, v[110:113]
	ds_write_b128 v207, v[114:117] offset:1152
	ds_write_b128 v207, v[118:121] offset:2304
	ds_write_b128 v207, v[122:125] offset:3456
	ds_write_b128 v207, v[126:129] offset:4608
	global_load_dwordx4 v[82:85], v198, s[42:43] offset:384
	global_load_dwordx4 v[86:89], v199, s[42:43] offset:384
	global_load_dwordx4 v[90:93], v200, s[42:43] offset:384
	global_load_dwordx4 v[94:97], v201, s[42:43] offset:384
	global_load_dwordx4 v[98:101], v198, s[44:45] offset:384
	global_load_dwordx4 v[102:105], v199, s[44:45] offset:384
	global_load_dwordx4 v[106:109], v200, s[44:45] offset:384
	global_load_dwordx4 v[110:113], v201, s[44:45] offset:384
	global_load_dwordx4 v[114:117], v202, s[44:45] offset:384
	global_load_dwordx4 v[118:121], v203, s[44:45] offset:384
	global_load_dwordx4 v[122:125], v204, s[44:45] offset:384
	global_load_dwordx4 v[126:129], v205, s[44:45] offset:384
	ds_read_b128 v[146:149], v208 offset:0
	ds_read_b128 v[150:153], v208 offset:2304
	ds_read_b128 v[154:157], v208 offset:4608
	ds_read_b128 v[158:161], v226
	ds_read_b128 v[162:165], v209 offset:1152
	ds_read_b128 v[166:169], v209 offset:3456
	ds_read_b128 v[170:173], v208 offset:64
	ds_read_b128 v[174:177], v208 offset:2368
	ds_read_b128 v[178:181], v208 offset:4672
	ds_read_b128 v[182:185], v226 offset:64
	ds_read_b128 v[186:189], v209 offset:1216
	ds_read_b128 v[190:193], v209 offset:3520
	s_waitcnt lgkmcnt(6)
	v_mfma_f32_16x16x32_bf16 v[8:11], v[146:149], v[154:157], v[8:11]
	v_mfma_f32_16x16x32_bf16 v[12:15], v[146:149], v[158:161], v[12:15]
	v_mfma_f32_16x16x32_bf16 v[16:19], v[146:149], v[162:165], v[16:19]
	v_mfma_f32_16x16x32_bf16 v[20:23], v[146:149], v[166:169], v[20:23]
	v_mfma_f32_16x16x32_bf16 v[24:27], v[150:153], v[154:157], v[24:27]
	v_mfma_f32_16x16x32_bf16 v[130:133], v[150:153], v[158:161], v[130:133]
	v_mfma_f32_16x16x32_bf16 v[134:137], v[150:153], v[162:165], v[134:137]
	v_mfma_f32_16x16x32_bf16 v[194:197], v[150:153], v[166:169], v[194:197]
	s_waitcnt lgkmcnt(0)
	v_mfma_f32_16x16x32_bf16 v[8:11], v[170:173], v[178:181], v[8:11]
	v_mfma_f32_16x16x32_bf16 v[12:15], v[170:173], v[182:185], v[12:15]
	v_mfma_f32_16x16x32_bf16 v[16:19], v[170:173], v[186:189], v[16:19]
	v_mfma_f32_16x16x32_bf16 v[20:23], v[170:173], v[190:193], v[20:23]
	v_mfma_f32_16x16x32_bf16 v[24:27], v[174:177], v[178:181], v[24:27]
	v_mfma_f32_16x16x32_bf16 v[130:133], v[174:177], v[182:185], v[130:133]
	v_mfma_f32_16x16x32_bf16 v[134:137], v[174:177], v[186:189], v[134:137]
	v_mfma_f32_16x16x32_bf16 v[194:197], v[174:177], v[190:193], v[194:197]
	s_waitcnt vmcnt(12)
	ds_write_b128 v206, v[34:37]
	ds_write_b128 v206, v[38:41] offset:1152
	ds_write_b128 v206, v[42:45] offset:2304
	ds_write_b128 v206, v[46:49] offset:3456
	ds_write_b128 v206, v[50:53] offset:4608
	ds_write_b128 v206, v[54:57] offset:5760
	ds_write_b128 v206, v[58:61] offset:6912
	ds_write_b128 v207, v[62:65]
	ds_write_b128 v207, v[66:69] offset:1152
	ds_write_b128 v207, v[70:73] offset:2304
	ds_write_b128 v207, v[74:77] offset:3456
	ds_write_b128 v207, v[78:81] offset:4608
	global_load_dwordx4 v[34:37], v198, s[42:43] offset:512
	global_load_dwordx4 v[38:41], v199, s[42:43] offset:512
	global_load_dwordx4 v[42:45], v200, s[42:43] offset:512
	global_load_dwordx4 v[46:49], v201, s[42:43] offset:512
	global_load_dwordx4 v[50:53], v198, s[44:45] offset:512
	global_load_dwordx4 v[54:57], v199, s[44:45] offset:512
	global_load_dwordx4 v[58:61], v200, s[44:45] offset:512
	global_load_dwordx4 v[62:65], v201, s[44:45] offset:512
	global_load_dwordx4 v[66:69], v202, s[44:45] offset:512
	global_load_dwordx4 v[70:73], v203, s[44:45] offset:512
	global_load_dwordx4 v[74:77], v204, s[44:45] offset:512
	global_load_dwordx4 v[78:81], v205, s[44:45] offset:512
	ds_read_b128 v[146:149], v208 offset:0
	ds_read_b128 v[150:153], v208 offset:2304
	ds_read_b128 v[154:157], v208 offset:4608
	ds_read_b128 v[158:161], v226
	ds_read_b128 v[162:165], v209 offset:1152
	ds_read_b128 v[166:169], v209 offset:3456
	ds_read_b128 v[170:173], v208 offset:64
	ds_read_b128 v[174:177], v208 offset:2368
	ds_read_b128 v[178:181], v208 offset:4672
	ds_read_b128 v[182:185], v226 offset:64
	ds_read_b128 v[186:189], v209 offset:1216
	ds_read_b128 v[190:193], v209 offset:3520
	s_waitcnt lgkmcnt(6)
	v_mfma_f32_16x16x32_bf16 v[8:11], v[146:149], v[154:157], v[8:11]
	v_mfma_f32_16x16x32_bf16 v[12:15], v[146:149], v[158:161], v[12:15]
	v_mfma_f32_16x16x32_bf16 v[16:19], v[146:149], v[162:165], v[16:19]
	v_mfma_f32_16x16x32_bf16 v[20:23], v[146:149], v[166:169], v[20:23]
	v_mfma_f32_16x16x32_bf16 v[24:27], v[150:153], v[154:157], v[24:27]
	v_mfma_f32_16x16x32_bf16 v[130:133], v[150:153], v[158:161], v[130:133]
	v_mfma_f32_16x16x32_bf16 v[134:137], v[150:153], v[162:165], v[134:137]
	v_mfma_f32_16x16x32_bf16 v[194:197], v[150:153], v[166:169], v[194:197]
	s_waitcnt lgkmcnt(0)
; #define MFMA16(a, b, c) __builtin_amdgcn_mfma_f32_16x16x32_bf16((a), (b), (c), 0, 0, 0)
; __device__ __forceinline__ void sample_out_block(LAS unsigned char* lds, const bf16_t* A, const bf16_t* Bt, int K, bf16_t* xb, float* sspart, int blk, int tid) {
;     ...
;         for (int k0 = 0; k0 < kq; k0 += 64) {
;             const int k1 = (k0 + 64 < kq) ? k0 + 64 : k0;
; #pragma unroll
;             for (int s = 0; s < 2; ++s) {
; #pragma unroll
;                 for (int ra = 0; ra < 2; ++ra) afn[s][ra] = *(const bf16x8*)(ap + (size_t)(16 * ra) * K + k1 + 32 * s);
; #pragma unroll
;                 for (int nt = 0; nt < 4; ++nt) bfn[s][nt] = *(const bf16x8*)(bp + (size_t)(16 * nt) * K + k1 + 32 * s);
;             }
; #pragma unroll
;             for (int s = 0; s < 2; ++s)
; #pragma unroll
;                 for (int ra = 0; ra < 2; ++ra)
; #pragma unroll
;                     for (int nt = 0; nt < 4; ++nt) acc[ra][nt] = MFMA16(af[s][ra], bf[s][nt], acc[ra][nt]);
; #pragma unroll
;             for (int s = 0; s < 2; ++s) {
; #pragma unroll
;                 for (int ra = 0; ra < 2; ++ra) af[s][ra] = afn[s][ra];
; #pragma unroll
;                 for (int nt = 0; nt < 4; ++nt) bf[s][nt] = bfn[s][nt];
;             }
;         }
	v_mfma_f32_16x16x32_bf16 v[8:11], v[170:173], v[178:181], v[8:11]
	v_mfma_f32_16x16x32_bf16 v[12:15], v[170:173], v[182:185], v[12:15]
	v_mfma_f32_16x16x32_bf16 v[16:19], v[170:173], v[186:189], v[16:19]
	v_mfma_f32_16x16x32_bf16 v[20:23], v[170:173], v[190:193], v[20:23]
	v_mfma_f32_16x16x32_bf16 v[24:27], v[174:177], v[178:181], v[24:27]
	v_mfma_f32_16x16x32_bf16 v[130:133], v[174:177], v[182:185], v[130:133]
	v_mfma_f32_16x16x32_bf16 v[134:137], v[174:177], v[186:189], v[134:137]
	v_mfma_f32_16x16x32_bf16 v[194:197], v[174:177], v[190:193], v[194:197]
	s_waitcnt vmcnt(12)
	ds_write_b128 v206, v[82:85]
	ds_write_b128 v206, v[86:89] offset:1152
	ds_write_b128 v206, v[90:93] offset:2304
	ds_write_b128 v206, v[94:97] offset:3456
	ds_write_b128 v206, v[98:101] offset:4608
	ds_write_b128 v206, v[102:105] offset:5760
	ds_write_b128 v206, v[106:109] offset:6912
	ds_write_b128 v207, v[110:113]
	ds_write_b128 v207, v[114:117] offset:1152
	ds_write_b128 v207, v[118:121] offset:2304
	ds_write_b128 v207, v[122:125] offset:3456
	ds_write_b128 v207, v[126:129] offset:4608
	global_load_dwordx4 v[82:85], v198, s[42:43] offset:640
	global_load_dwordx4 v[86:89], v199, s[42:43] offset:640
	global_load_dwordx4 v[90:93], v200, s[42:43] offset:640
	global_load_dwordx4 v[94:97], v201, s[42:43] offset:640
	global_load_dwordx4 v[98:101], v198, s[44:45] offset:640
	global_load_dwordx4 v[102:105], v199, s[44:45] offset:640
	global_load_dwordx4 v[106:109], v200, s[44:45] offset:640
	global_load_dwordx4 v[110:113], v201, s[44:45] offset:640
	global_load_dwordx4 v[114:117], v202, s[44:45] offset:640
	global_load_dwordx4 v[118:121], v203, s[44:45] offset:640
	global_load_dwordx4 v[122:125], v204, s[44:45] offset:640
	global_load_dwordx4 v[126:129], v205, s[44:45] offset:640
	ds_read_b128 v[146:149], v208 offset:0
	ds_read_b128 v[150:153], v208 offset:2304
	ds_read_b128 v[154:157], v208 offset:4608
	ds_read_b128 v[158:161], v226
	ds_read_b128 v[162:165], v209 offset:1152
	ds_read_b128 v[166:169], v209 offset:3456
	ds_read_b128 v[170:173], v208 offset:64
	ds_read_b128 v[174:177], v208 offset:2368
	ds_read_b128 v[178:181], v208 offset:4672
	ds_read_b128 v[182:185], v226 offset:64
	ds_read_b128 v[186:189], v209 offset:1216
	ds_read_b128 v[190:193], v209 offset:3520
	s_waitcnt lgkmcnt(6)
	v_mfma_f32_16x16x32_bf16 v[8:11], v[146:149], v[154:157], v[8:11]
	v_mfma_f32_16x16x32_bf16 v[12:15], v[146:149], v[158:161], v[12:15]
	v_mfma_f32_16x16x32_bf16 v[16:19], v[146:149], v[162:165], v[16:19]
	v_mfma_f32_16x16x32_bf16 v[20:23], v[146:149], v[166:169], v[20:23]
	v_mfma_f32_16x16x32_bf16 v[24:27], v[150:153], v[154:157], v[24:27]
	v_mfma_f32_16x16x32_bf16 v[130:133], v[150:153], v[158:161], v[130:133]
	v_mfma_f32_16x16x32_bf16 v[134:137], v[150:153], v[162:165], v[134:137]
	v_mfma_f32_16x16x32_bf16 v[194:197], v[150:153], v[166:169], v[194:197]
	s_waitcnt lgkmcnt(0)
	v_mfma_f32_16x16x32_bf16 v[8:11], v[170:173], v[178:181], v[8:11]
	v_mfma_f32_16x16x32_bf16 v[12:15], v[170:173], v[182:185], v[12:15]
	v_mfma_f32_16x16x32_bf16 v[16:19], v[170:173], v[186:189], v[16:19]
	v_mfma_f32_16x16x32_bf16 v[20:23], v[170:173], v[190:193], v[20:23]
	v_mfma_f32_16x16x32_bf16 v[24:27], v[174:177], v[178:181], v[24:27]
	v_mfma_f32_16x16x32_bf16 v[130:133], v[174:177], v[182:185], v[130:133]
	v_mfma_f32_16x16x32_bf16 v[134:137], v[174:177], v[186:189], v[134:137]
	v_mfma_f32_16x16x32_bf16 v[194:197], v[174:177], v[190:193], v[194:197]
	s_waitcnt vmcnt(12)
	ds_write_b128 v206, v[34:37]
	ds_write_b128 v206, v[38:41] offset:1152
	ds_write_b128 v206, v[42:45] offset:2304
	ds_write_b128 v206, v[46:49] offset:3456
	ds_write_b128 v206, v[50:53] offset:4608
	ds_write_b128 v206, v[54:57] offset:5760
	ds_write_b128 v206, v[58:61] offset:6912
	ds_write_b128 v207, v[62:65]
	ds_write_b128 v207, v[66:69] offset:1152
	ds_write_b128 v207, v[70:73] offset:2304
	ds_write_b128 v207, v[74:77] offset:3456
	ds_write_b128 v207, v[78:81] offset:4608
	global_load_dwordx4 v[34:37], v198, s[42:43] offset:768
	global_load_dwordx4 v[38:41], v199, s[42:43] offset:768
	global_load_dwordx4 v[42:45], v200, s[42:43] offset:768
	global_load_dwordx4 v[46:49], v201, s[42:43] offset:768
	global_load_dwordx4 v[50:53], v198, s[44:45] offset:768
	global_load_dwordx4 v[54:57], v199, s[44:45] offset:768
	global_load_dwordx4 v[58:61], v200, s[44:45] offset:768
	global_load_dwordx4 v[62:65], v201, s[44:45] offset:768
	global_load_dwordx4 v[66:69], v202, s[44:45] offset:768
	global_load_dwordx4 v[70:73], v203, s[44:45] offset:768
	global_load_dwordx4 v[74:77], v204, s[44:45] offset:768
	global_load_dwordx4 v[78:81], v205, s[44:45] offset:768
	ds_read_b128 v[146:149], v208 offset:0
	ds_read_b128 v[150:153], v208 offset:2304
	ds_read_b128 v[154:157], v208 offset:4608
	ds_read_b128 v[158:161], v226
	ds_read_b128 v[162:165], v209 offset:1152
	ds_read_b128 v[166:169], v209 offset:3456
	ds_read_b128 v[170:173], v208 offset:64
	ds_read_b128 v[174:177], v208 offset:2368
	ds_read_b128 v[178:181], v208 offset:4672
	ds_read_b128 v[182:185], v226 offset:64
	ds_read_b128 v[186:189], v209 offset:1216
	ds_read_b128 v[190:193], v209 offset:3520
	s_waitcnt lgkmcnt(6)
	v_mfma_f32_16x16x32_bf16 v[8:11], v[146:149], v[154:157], v[8:11]
	v_mfma_f32_16x16x32_bf16 v[12:15], v[146:149], v[158:161], v[12:15]
	v_mfma_f32_16x16x32_bf16 v[16:19], v[146:149], v[162:165], v[16:19]
	v_mfma_f32_16x16x32_bf16 v[20:23], v[146:149], v[166:169], v[20:23]
	v_mfma_f32_16x16x32_bf16 v[24:27], v[150:153], v[154:157], v[24:27]
	v_mfma_f32_16x16x32_bf16 v[130:133], v[150:153], v[158:161], v[130:133]
	v_mfma_f32_16x16x32_bf16 v[134:137], v[150:153], v[162:165], v[134:137]
	v_mfma_f32_16x16x32_bf16 v[194:197], v[150:153], v[166:169], v[194:197]
	s_waitcnt lgkmcnt(0)
; #define MFMA16(a, b, c) __builtin_amdgcn_mfma_f32_16x16x32_bf16((a), (b), (c), 0, 0, 0)
; __device__ __forceinline__ void sample_out_block(LAS unsigned char* lds, const bf16_t* A, const bf16_t* Bt, int K, bf16_t* xb, float* sspart, int blk, int tid) {
;     ...
;         for (int k0 = 0; k0 < kq; k0 += 64) {
;             const int k1 = (k0 + 64 < kq) ? k0 + 64 : k0;
; #pragma unroll
;             for (int s = 0; s < 2; ++s) {
; #pragma unroll
;                 for (int ra = 0; ra < 2; ++ra) afn[s][ra] = *(const bf16x8*)(ap + (size_t)(16 * ra) * K + k1 + 32 * s);
; #pragma unroll
;                 for (int nt = 0; nt < 4; ++nt) bfn[s][nt] = *(const bf16x8*)(bp + (size_t)(16 * nt) * K + k1 + 32 * s);
;             }
; #pragma unroll
;             for (int s = 0; s < 2; ++s)
; #pragma unroll
;                 for (int ra = 0; ra < 2; ++ra)
; #pragma unroll
;                     for (int nt = 0; nt < 4; ++nt) acc[ra][nt] = MFMA16(af[s][ra], bf[s][nt], acc[ra][nt]);
; #pragma unroll
;             for (int s = 0; s < 2; ++s) {
; #pragma unroll
;                 for (int ra = 0; ra < 2; ++ra) af[s][ra] = afn[s][ra];
; #pragma unroll
;                 for (int nt = 0; nt < 4; ++nt) bf[s][nt] = bfn[s][nt];
;             }
;         }
	v_mfma_f32_16x16x32_bf16 v[8:11], v[170:173], v[178:181], v[8:11]
	v_mfma_f32_16x16x32_bf16 v[12:15], v[170:173], v[182:185], v[12:15]
	v_mfma_f32_16x16x32_bf16 v[16:19], v[170:173], v[186:189], v[16:19]
	v_mfma_f32_16x16x32_bf16 v[20:23], v[170:173], v[190:193], v[20:23]
	v_mfma_f32_16x16x32_bf16 v[24:27], v[174:177], v[178:181], v[24:27]
	v_mfma_f32_16x16x32_bf16 v[130:133], v[174:177], v[182:185], v[130:133]
	v_mfma_f32_16x16x32_bf16 v[134:137], v[174:177], v[186:189], v[134:137]
	v_mfma_f32_16x16x32_bf16 v[194:197], v[174:177], v[190:193], v[194:197]
	s_waitcnt vmcnt(12)
	ds_write_b128 v206, v[82:85]
	ds_write_b128 v206, v[86:89] offset:1152
	ds_write_b128 v206, v[90:93] offset:2304
	ds_write_b128 v206, v[94:97] offset:3456
	ds_write_b128 v206, v[98:101] offset:4608
	ds_write_b128 v206, v[102:105] offset:5760
	ds_write_b128 v206, v[106:109] offset:6912
	ds_write_b128 v207, v[110:113]
	ds_write_b128 v207, v[114:117] offset:1152
	ds_write_b128 v207, v[118:121] offset:2304
	ds_write_b128 v207, v[122:125] offset:3456
	ds_write_b128 v207, v[126:129] offset:4608
	global_load_dwordx4 v[82:85], v198, s[42:43] offset:896
	global_load_dwordx4 v[86:89], v199, s[42:43] offset:896
	global_load_dwordx4 v[90:93], v200, s[42:43] offset:896
	global_load_dwordx4 v[94:97], v201, s[42:43] offset:896
	global_load_dwordx4 v[98:101], v198, s[44:45] offset:896
	global_load_dwordx4 v[102:105], v199, s[44:45] offset:896
	global_load_dwordx4 v[106:109], v200, s[44:45] offset:896
	global_load_dwordx4 v[110:113], v201, s[44:45] offset:896
	global_load_dwordx4 v[114:117], v202, s[44:45] offset:896
	global_load_dwordx4 v[118:121], v203, s[44:45] offset:896
	global_load_dwordx4 v[122:125], v204, s[44:45] offset:896
	global_load_dwordx4 v[126:129], v205, s[44:45] offset:896
	ds_read_b128 v[146:149], v208 offset:0
	ds_read_b128 v[150:153], v208 offset:2304
	ds_read_b128 v[154:157], v208 offset:4608
	ds_read_b128 v[158:161], v226
	ds_read_b128 v[162:165], v209 offset:1152
	ds_read_b128 v[166:169], v209 offset:3456
	ds_read_b128 v[170:173], v208 offset:64
	ds_read_b128 v[174:177], v208 offset:2368
	ds_read_b128 v[178:181], v208 offset:4672
	ds_read_b128 v[182:185], v226 offset:64
	ds_read_b128 v[186:189], v209 offset:1216
	ds_read_b128 v[190:193], v209 offset:3520
	s_waitcnt lgkmcnt(6)
	v_mfma_f32_16x16x32_bf16 v[8:11], v[146:149], v[154:157], v[8:11]
	v_mfma_f32_16x16x32_bf16 v[12:15], v[146:149], v[158:161], v[12:15]
	v_mfma_f32_16x16x32_bf16 v[16:19], v[146:149], v[162:165], v[16:19]
	v_mfma_f32_16x16x32_bf16 v[20:23], v[146:149], v[166:169], v[20:23]
	v_mfma_f32_16x16x32_bf16 v[24:27], v[150:153], v[154:157], v[24:27]
	v_mfma_f32_16x16x32_bf16 v[130:133], v[150:153], v[158:161], v[130:133]
	v_mfma_f32_16x16x32_bf16 v[134:137], v[150:153], v[162:165], v[134:137]
	v_mfma_f32_16x16x32_bf16 v[194:197], v[150:153], v[166:169], v[194:197]
	s_waitcnt lgkmcnt(0)
	v_mfma_f32_16x16x32_bf16 v[8:11], v[170:173], v[178:181], v[8:11]
	v_mfma_f32_16x16x32_bf16 v[12:15], v[170:173], v[182:185], v[12:15]
	v_mfma_f32_16x16x32_bf16 v[16:19], v[170:173], v[186:189], v[16:19]
	v_mfma_f32_16x16x32_bf16 v[20:23], v[170:173], v[190:193], v[20:23]
	v_mfma_f32_16x16x32_bf16 v[24:27], v[174:177], v[178:181], v[24:27]
	v_mfma_f32_16x16x32_bf16 v[130:133], v[174:177], v[182:185], v[130:133]
	v_mfma_f32_16x16x32_bf16 v[134:137], v[174:177], v[186:189], v[134:137]
	v_mfma_f32_16x16x32_bf16 v[194:197], v[174:177], v[190:193], v[194:197]
	s_waitcnt vmcnt(12)
	ds_write_b128 v206, v[34:37]
	ds_write_b128 v206, v[38:41] offset:1152
	ds_write_b128 v206, v[42:45] offset:2304
	ds_write_b128 v206, v[46:49] offset:3456
	ds_write_b128 v206, v[50:53] offset:4608
	ds_write_b128 v206, v[54:57] offset:5760
	ds_write_b128 v206, v[58:61] offset:6912
	ds_write_b128 v207, v[62:65]
	ds_write_b128 v207, v[66:69] offset:1152
	ds_write_b128 v207, v[70:73] offset:2304
	ds_write_b128 v207, v[74:77] offset:3456
	ds_write_b128 v207, v[78:81] offset:4608
	ds_read_b128 v[146:149], v208 offset:0
	ds_read_b128 v[150:153], v208 offset:2304
	ds_read_b128 v[154:157], v208 offset:4608
	ds_read_b128 v[158:161], v226
	ds_read_b128 v[162:165], v209 offset:1152
	ds_read_b128 v[166:169], v209 offset:3456
	ds_read_b128 v[170:173], v208 offset:64
	ds_read_b128 v[174:177], v208 offset:2368
	ds_read_b128 v[178:181], v208 offset:4672
	ds_read_b128 v[182:185], v226 offset:64
	ds_read_b128 v[186:189], v209 offset:1216
	ds_read_b128 v[190:193], v209 offset:3520
	s_waitcnt lgkmcnt(6)
	v_mfma_f32_16x16x32_bf16 v[8:11], v[146:149], v[154:157], v[8:11]
	v_mfma_f32_16x16x32_bf16 v[12:15], v[146:149], v[158:161], v[12:15]
	v_mfma_f32_16x16x32_bf16 v[16:19], v[146:149], v[162:165], v[16:19]
	v_mfma_f32_16x16x32_bf16 v[20:23], v[146:149], v[166:169], v[20:23]
	v_mfma_f32_16x16x32_bf16 v[24:27], v[150:153], v[154:157], v[24:27]
	v_mfma_f32_16x16x32_bf16 v[130:133], v[150:153], v[158:161], v[130:133]
	v_mfma_f32_16x16x32_bf16 v[134:137], v[150:153], v[162:165], v[134:137]
	v_mfma_f32_16x16x32_bf16 v[194:197], v[150:153], v[166:169], v[194:197]
	s_waitcnt lgkmcnt(0)
	v_mfma_f32_16x16x32_bf16 v[8:11], v[170:173], v[178:181], v[8:11]
	v_mfma_f32_16x16x32_bf16 v[12:15], v[170:173], v[182:185], v[12:15]
	v_mfma_f32_16x16x32_bf16 v[16:19], v[170:173], v[186:189], v[16:19]
	v_mfma_f32_16x16x32_bf16 v[20:23], v[170:173], v[190:193], v[20:23]
	v_mfma_f32_16x16x32_bf16 v[24:27], v[174:177], v[178:181], v[24:27]
	v_mfma_f32_16x16x32_bf16 v[130:133], v[174:177], v[182:185], v[130:133]
	v_mfma_f32_16x16x32_bf16 v[134:137], v[174:177], v[186:189], v[134:137]
	v_mfma_f32_16x16x32_bf16 v[194:197], v[174:177], v[190:193], v[194:197]
	s_waitcnt vmcnt(0)
; #define LAS __attribute__((address_space(3)))
; __device__ __forceinline__ float bf1(bf16_t h) { return __uint_as_float((unsigned)h << 16); }
; __device__ __forceinline__ bf16_t f2bf(float f) { return (bf16_t)(pk2(f, 0.f) & 0xffffu); }
; __device__ __forceinline__ void sample_out_block(LAS unsigned char* lds, const bf16_t* A, const bf16_t* Bt, int K, bf16_t* xb, float* sspart, int blk, int tid) {
;     ...
;     LAS f32x4* part = (LAS f32x4*)lds;
; #pragma unroll
;     for (int ra = 0; ra < 2; ++ra)
; #pragma unroll
;         for (int nt = 0; nt < 4; ++nt) part[(wave * 8 + ra * 4 + nt) * 64 + lane] = acc[ra][nt];
;     __syncthreads();
;     if (wave < 2) {
;         const int ra = wave;
;         f32x4 sum[4];
; #pragma unroll
;         for (int nt = 0; nt < 4; ++nt) {
;             sum[nt] = part[(0 * 8 + ra * 4 + nt) * 64 + lane];
; #pragma unroll
;             for (int w = 1; w < 8; ++w) sum[nt] += part[(w * 8 + ra * 4 + nt) * 64 + lane];
;         }
;         float ss[4] = {0.f, 0.f, 0.f, 0.f};
; #pragma unroll
;         for (int j = 0; j < 4; ++j)
; #pragma unroll
;             for (int nt = 0; nt < 4; ++nt) {
;                 bf16_t* xp = xb + (size_t)(r0 + 16 * ra + 4 * g + j) * 2048 + 64 * cg + 16 * nt + l15;
;                 const bf16_t nv = f2bf(bf1(*xp) + sum[nt][j]);
	ds_write_b128 v206, v[82:85]
	ds_write_b128 v206, v[86:89] offset:1152
	ds_write_b128 v206, v[90:93] offset:2304
	ds_write_b128 v206, v[94:97] offset:3456
	ds_write_b128 v206, v[98:101] offset:4608
	ds_write_b128 v206, v[102:105] offset:5760
	ds_write_b128 v206, v[106:109] offset:6912
	ds_write_b128 v207, v[110:113]
	ds_write_b128 v207, v[114:117] offset:1152
	ds_write_b128 v207, v[118:121] offset:2304
	ds_write_b128 v207, v[122:125] offset:3456
	ds_write_b128 v207, v[126:129] offset:4608
	ds_read_b128 v[146:149], v208 offset:0
	ds_read_b128 v[150:153], v208 offset:2304
	ds_read_b128 v[154:157], v208 offset:4608
	ds_read_b128 v[158:161], v226
	ds_read_b128 v[162:165], v209 offset:1152
	ds_read_b128 v[166:169], v209 offset:3456
	ds_read_b128 v[170:173], v208 offset:64
	ds_read_b128 v[174:177], v208 offset:2368
	ds_read_b128 v[178:181], v208 offset:4672
	ds_read_b128 v[182:185], v226 offset:64
	ds_read_b128 v[186:189], v209 offset:1216
	ds_read_b128 v[190:193], v209 offset:3520
	s_waitcnt lgkmcnt(6)
	v_mfma_f32_16x16x32_bf16 v[8:11], v[146:149], v[154:157], v[8:11]
	v_mfma_f32_16x16x32_bf16 v[12:15], v[146:149], v[158:161], v[12:15]
	v_mfma_f32_16x16x32_bf16 v[16:19], v[146:149], v[162:165], v[16:19]
	v_mfma_f32_16x16x32_bf16 v[20:23], v[146:149], v[166:169], v[20:23]
	v_mfma_f32_16x16x32_bf16 v[24:27], v[150:153], v[154:157], v[24:27]
	v_mfma_f32_16x16x32_bf16 v[130:133], v[150:153], v[158:161], v[130:133]
	v_mfma_f32_16x16x32_bf16 v[134:137], v[150:153], v[162:165], v[134:137]
	v_mfma_f32_16x16x32_bf16 v[194:197], v[150:153], v[166:169], v[194:197]
	s_waitcnt lgkmcnt(0)
	v_mfma_f32_16x16x32_bf16 v[8:11], v[170:173], v[178:181], v[8:11]
	v_mfma_f32_16x16x32_bf16 v[12:15], v[170:173], v[182:185], v[12:15]
	v_mfma_f32_16x16x32_bf16 v[16:19], v[170:173], v[186:189], v[16:19]
	v_mfma_f32_16x16x32_bf16 v[20:23], v[170:173], v[190:193], v[20:23]
	v_mfma_f32_16x16x32_bf16 v[24:27], v[174:177], v[178:181], v[24:27]
	v_mfma_f32_16x16x32_bf16 v[130:133], v[174:177], v[182:185], v[130:133]
	v_mfma_f32_16x16x32_bf16 v[134:137], v[174:177], v[186:189], v[134:137]
	v_mfma_f32_16x16x32_bf16 v[194:197], v[174:177], v[190:193], v[194:197]
	s_nop 7
	s_nop 7
	ds_write_b128 v32, v[8:11]
	ds_write_b128 v32, v[12:15] offset:1024
	ds_write_b128 v32, v[16:19] offset:2048
	ds_write_b128 v32, v[20:23] offset:3072
	ds_write_b128 v32, v[24:27] offset:4096
	ds_write_b128 v32, v[130:133] offset:5120
	ds_write_b128 v32, v[134:137] offset:6144
	ds_write_b128 v32, v[194:197] offset:7168
	s_waitcnt lgkmcnt(0)
	s_barrier
	s_and_saveexec_b64 s[10:11], s[6:7]
	s_cbranch_execz .LBB0_541
	v_add_u32_e32 v170, s27, v31
	v_lshlrev_b32_e32 v170, 12, v170
	s_lshl_b32 s36, s35, 1
	v_add_u32_e32 v170, s36, v170
	v_mov_b32_e32 v171, 0
	s_mov_b64 s[38:39], 0x1000
	v_lshl_add_u64 v[162:163], v[6:7], 0, v[170:171]
	v_lshl_add_u64 v[164:165], v[162:163], 0, s[38:39]
	v_lshl_add_u64 v[166:167], v[164:165], 0, s[38:39]
	v_lshl_add_u64 v[168:169], v[166:167], 0, s[38:39]
	global_load_ushort v146, v[162:163], off
	global_load_ushort v147, v[162:163], off offset:32
	global_load_ushort v148, v[162:163], off offset:64
	global_load_ushort v149, v[162:163], off offset:96
	global_load_ushort v150, v[164:165], off
	global_load_ushort v151, v[164:165], off offset:32
	global_load_ushort v152, v[164:165], off offset:64
	global_load_ushort v153, v[164:165], off offset:96
	global_load_ushort v154, v[166:167], off
	global_load_ushort v155, v[166:167], off offset:32
	global_load_ushort v156, v[166:167], off offset:64
	global_load_ushort v157, v[166:167], off offset:96
	global_load_ushort v158, v[168:169], off
	global_load_ushort v159, v[168:169], off offset:32
	global_load_ushort v160, v[168:169], off offset:64
	global_load_ushort v161, v[168:169], off offset:96
	ds_read_b128 v[38:41], v33
	ds_read_b128 v[42:45], v33 offset:8192
	ds_read_b128 v[46:49], v33 offset:16384
	ds_read_b128 v[50:53], v33 offset:24576
	ds_read_b128 v[54:57], v33 offset:32768
	ds_read_b128 v[58:61], v33 offset:40960
	ds_read_b128 v[62:65], v33 offset:49152
	ds_read_b128 v[66:69], v33 offset:57344
	ds_read_b128 v[70:73], v33 offset:1024
	ds_read_b128 v[74:77], v33 offset:9216
	ds_read_b128 v[78:81], v33 offset:17408
	ds_read_b128 v[82:85], v33 offset:25600
	ds_read_b128 v[86:89], v33 offset:33792
	ds_read_b128 v[90:93], v33 offset:41984
	ds_read_b128 v[94:97], v33 offset:50176
	ds_read_b128 v[98:101], v33 offset:58368
	ds_read_b128 v[102:105], v33 offset:2048
	ds_read_b128 v[106:109], v33 offset:10240
	ds_read_b128 v[110:113], v33 offset:18432
	ds_read_b128 v[114:117], v33 offset:26624
	ds_read_b128 v[118:121], v33 offset:34816
	ds_read_b128 v[122:125], v33 offset:43008
	ds_read_b128 v[126:129], v33 offset:51200
	ds_read_b128 v[172:175], v33 offset:59392
	ds_read_b128 v[176:179], v33 offset:3072
	ds_read_b128 v[180:183], v33 offset:11264
	ds_read_b128 v[184:187], v33 offset:19456
	ds_read_b128 v[188:191], v33 offset:60416
	ds_read_b128 v[192:195], v33 offset:27648
	ds_read_b128 v[196:199], v33 offset:35840
	ds_read_b128 v[200:203], v33 offset:44032
	ds_read_b128 v[204:207], v33 offset:52224
	s_waitcnt lgkmcnt(0)
	v_mov_b32_e32 v8, v38
	v_mov_b32_e32 v9, v39
	v_mov_b32_e32 v10, v40
	v_mov_b32_e32 v11, v41
	v_mov_b32_e32 v12, v42
	v_mov_b32_e32 v13, v43
	v_mov_b32_e32 v14, v44
	v_mov_b32_e32 v15, v45
	s_lshl_b32 s80, s35, 1
	v_lshl_add_u64 v[28:29], v[6:7], 0, s[80:81]
	s_lshl_b32 s12, s26, 2
	s_add_u32 s12, s22, s12
	s_waitcnt lgkmcnt(0)
	v_pk_add_f32 v[14:15], v[10:11], v[14:15]
	v_pk_add_f32 v[12:13], v[8:9], v[12:13]
	v_mov_b32_e32 v8, v46
	v_mov_b32_e32 v9, v47
	v_mov_b32_e32 v10, v48
	v_mov_b32_e32 v11, v49
	s_addc_u32 s13, s23, 0
	s_waitcnt lgkmcnt(0)
; __device__ __forceinline__ void sample_out_block(LAS unsigned char* lds, const bf16_t* A, const bf16_t* Bt, int K, bf16_t* xb, float* sspart, int blk, int tid) {
;     ...
;         for (int nt = 0; nt < 4; ++nt) {
;             sum[nt] = part[(0 * 8 + ra * 4 + nt) * 64 + lane];
; #pragma unroll
;             for (int w = 1; w < 8; ++w) sum[nt] += part[(w * 8 + ra * 4 + nt) * 64 + lane];
;         }
	v_pk_add_f32 v[14:15], v[14:15], v[10:11]
	v_pk_add_f32 v[12:13], v[12:13], v[8:9]
	v_mov_b32_e32 v8, v50
	v_mov_b32_e32 v9, v51
	v_mov_b32_e32 v10, v52
	v_mov_b32_e32 v11, v53
	s_waitcnt lgkmcnt(0)
	v_pk_add_f32 v[14:15], v[14:15], v[10:11]
	v_pk_add_f32 v[12:13], v[12:13], v[8:9]
	v_mov_b32_e32 v8, v54
	v_mov_b32_e32 v9, v55
	v_mov_b32_e32 v10, v56
	v_mov_b32_e32 v11, v57
	s_waitcnt lgkmcnt(0)
	v_pk_add_f32 v[14:15], v[14:15], v[10:11]
	v_pk_add_f32 v[12:13], v[12:13], v[8:9]
	v_mov_b32_e32 v8, v58
	v_mov_b32_e32 v9, v59
	v_mov_b32_e32 v10, v60
	v_mov_b32_e32 v11, v61
	s_waitcnt lgkmcnt(0)
	v_pk_add_f32 v[14:15], v[14:15], v[10:11]
	v_pk_add_f32 v[12:13], v[12:13], v[8:9]
	v_mov_b32_e32 v8, v62
	v_mov_b32_e32 v9, v63
	v_mov_b32_e32 v10, v64
	v_mov_b32_e32 v11, v65
	s_waitcnt lgkmcnt(0)
	v_pk_add_f32 v[14:15], v[14:15], v[10:11]
	v_pk_add_f32 v[16:17], v[12:13], v[8:9]
	v_mov_b32_e32 v8, v66
	v_mov_b32_e32 v9, v67
	v_mov_b32_e32 v10, v68
	v_mov_b32_e32 v11, v69
	s_waitcnt lgkmcnt(0)
	v_pk_add_f32 v[12:13], v[14:15], v[10:11]
	v_pk_add_f32 v[20:21], v[16:17], v[8:9]
	v_mov_b32_e32 v8, v70
	v_mov_b32_e32 v9, v71
	v_mov_b32_e32 v10, v72
	v_mov_b32_e32 v11, v73
	v_mov_b32_e32 v14, v74
	v_mov_b32_e32 v15, v75
	v_mov_b32_e32 v16, v76
	v_mov_b32_e32 v17, v77
	s_waitcnt lgkmcnt(0)
	v_pk_add_f32 v[16:17], v[10:11], v[16:17]
	v_pk_add_f32 v[14:15], v[8:9], v[14:15]
	v_mov_b32_e32 v8, v78
	v_mov_b32_e32 v9, v79
	v_mov_b32_e32 v10, v80
	v_mov_b32_e32 v11, v81
	s_waitcnt lgkmcnt(0)
	v_pk_add_f32 v[16:17], v[16:17], v[10:11]
	v_pk_add_f32 v[14:15], v[14:15], v[8:9]
	v_mov_b32_e32 v8, v82
	v_mov_b32_e32 v9, v83
	v_mov_b32_e32 v10, v84
	v_mov_b32_e32 v11, v85
	s_waitcnt lgkmcnt(0)
	v_pk_add_f32 v[16:17], v[16:17], v[10:11]
	v_pk_add_f32 v[14:15], v[14:15], v[8:9]
	v_mov_b32_e32 v8, v86
	v_mov_b32_e32 v9, v87
	v_mov_b32_e32 v10, v88
	v_mov_b32_e32 v11, v89
	s_waitcnt lgkmcnt(0)
	v_pk_add_f32 v[16:17], v[16:17], v[10:11]
	v_pk_add_f32 v[14:15], v[14:15], v[8:9]
	v_mov_b32_e32 v8, v90
	v_mov_b32_e32 v9, v91
	v_mov_b32_e32 v10, v92
	v_mov_b32_e32 v11, v93
	s_waitcnt lgkmcnt(0)
	v_pk_add_f32 v[16:17], v[16:17], v[10:11]
	v_pk_add_f32 v[14:15], v[14:15], v[8:9]
	v_mov_b32_e32 v8, v94
	v_mov_b32_e32 v9, v95
	v_mov_b32_e32 v10, v96
	v_mov_b32_e32 v11, v97
	s_waitcnt lgkmcnt(0)
	v_pk_add_f32 v[16:17], v[16:17], v[10:11]
	v_pk_add_f32 v[14:15], v[14:15], v[8:9]
	v_mov_b32_e32 v8, v98
	v_mov_b32_e32 v9, v99
	v_mov_b32_e32 v10, v100
	v_mov_b32_e32 v11, v101
	s_waitcnt lgkmcnt(0)
	v_pk_add_f32 v[18:19], v[16:17], v[10:11]
	v_pk_add_f32 v[26:27], v[14:15], v[8:9]
	v_mov_b32_e32 v8, v102
	v_mov_b32_e32 v9, v103
	v_mov_b32_e32 v10, v104
	v_mov_b32_e32 v11, v105
	v_mov_b32_e32 v14, v106
	v_mov_b32_e32 v15, v107
	v_mov_b32_e32 v16, v108
	v_mov_b32_e32 v17, v109
	s_waitcnt lgkmcnt(0)
	v_pk_add_f32 v[16:17], v[10:11], v[16:17]
	v_pk_add_f32 v[14:15], v[8:9], v[14:15]
	v_mov_b32_e32 v8, v110
	v_mov_b32_e32 v9, v111
	v_mov_b32_e32 v10, v112
	v_mov_b32_e32 v11, v113
	s_waitcnt lgkmcnt(0)
	v_pk_add_f32 v[16:17], v[16:17], v[10:11]
	v_pk_add_f32 v[14:15], v[14:15], v[8:9]
	v_mov_b32_e32 v8, v114
	v_mov_b32_e32 v9, v115
	v_mov_b32_e32 v10, v116
	v_mov_b32_e32 v11, v117
	s_waitcnt lgkmcnt(0)
	v_pk_add_f32 v[16:17], v[16:17], v[10:11]
	v_pk_add_f32 v[14:15], v[14:15], v[8:9]
	v_mov_b32_e32 v8, v118
	v_mov_b32_e32 v9, v119
	v_mov_b32_e32 v10, v120
	v_mov_b32_e32 v11, v121
	s_waitcnt lgkmcnt(0)
	v_pk_add_f32 v[16:17], v[16:17], v[10:11]
	v_pk_add_f32 v[14:15], v[14:15], v[8:9]
	v_mov_b32_e32 v8, v122
	v_mov_b32_e32 v9, v123
	v_mov_b32_e32 v10, v124
	v_mov_b32_e32 v11, v125
	s_waitcnt lgkmcnt(0)
	v_pk_add_f32 v[16:17], v[16:17], v[10:11]
	v_pk_add_f32 v[14:15], v[14:15], v[8:9]
	v_mov_b32_e32 v8, v126
	v_mov_b32_e32 v9, v127
	v_mov_b32_e32 v10, v128
	v_mov_b32_e32 v11, v129
	s_waitcnt lgkmcnt(0)
	v_pk_add_f32 v[16:17], v[16:17], v[10:11]
	v_pk_add_f32 v[14:15], v[14:15], v[8:9]
	v_mov_b32_e32 v8, v172
	v_mov_b32_e32 v9, v173
	v_mov_b32_e32 v10, v174
	v_mov_b32_e32 v11, v175
	s_waitcnt lgkmcnt(0)
	v_pk_add_f32 v[16:17], v[16:17], v[10:11]
	v_pk_add_f32 v[24:25], v[14:15], v[8:9]
	v_mov_b32_e32 v8, v176
	v_mov_b32_e32 v9, v177
	v_mov_b32_e32 v10, v178
	v_mov_b32_e32 v11, v179
	v_mov_b32_e32 v34, v180
	v_mov_b32_e32 v35, v181
	v_mov_b32_e32 v36, v182
	v_mov_b32_e32 v37, v183
	s_waitcnt lgkmcnt(0)
	v_pk_add_f32 v[14:15], v[10:11], v[36:37]
	v_pk_add_f32 v[22:23], v[8:9], v[34:35]
	v_mov_b32_e32 v8, v184
	v_mov_b32_e32 v9, v185
	v_mov_b32_e32 v10, v186
	v_mov_b32_e32 v11, v187
	v_mov_b32_e32 v34, v188
	v_mov_b32_e32 v35, v189
	v_mov_b32_e32 v36, v190
	v_mov_b32_e32 v37, v191
	s_waitcnt lgkmcnt(1)
	v_pk_add_f32 v[14:15], v[14:15], v[10:11]
	v_pk_add_f32 v[22:23], v[22:23], v[8:9]
	v_mov_b32_e32 v8, v192
	v_mov_b32_e32 v9, v193
	v_mov_b32_e32 v10, v194
	v_mov_b32_e32 v11, v195
	s_waitcnt lgkmcnt(0)
	v_pk_add_f32 v[14:15], v[14:15], v[10:11]
	v_pk_add_f32 v[22:23], v[22:23], v[8:9]
	v_mov_b32_e32 v8, v196
	v_mov_b32_e32 v9, v197
	v_mov_b32_e32 v10, v198
	v_mov_b32_e32 v11, v199
	s_waitcnt lgkmcnt(0)
; __device__ __forceinline__ float bf1(bf16_t h) { return __uint_as_float((unsigned)h << 16); }
; __device__ __forceinline__ bf16_t f2bf(float f) { return (bf16_t)(pk2(f, 0.f) & 0xffffu); }
; __device__ __forceinline__ void sample_out_block(LAS unsigned char* lds, const bf16_t* A, const bf16_t* Bt, int K, bf16_t* xb, float* sspart, int blk, int tid) {
;     ...
;             for (int w = 1; w < 8; ++w) sum[nt] += part[(w * 8 + ra * 4 + nt) * 64 + lane];
;         }
;         float ss[4] = {0.f, 0.f, 0.f, 0.f};
; #pragma unroll
;         for (int j = 0; j < 4; ++j)
; #pragma unroll
;             for (int nt = 0; nt < 4; ++nt) {
;                 bf16_t* xp = xb + (size_t)(r0 + 16 * ra + 4 * g + j) * 2048 + 64 * cg + 16 * nt + l15;
;                 const bf16_t nv = f2bf(bf1(*xp) + sum[nt][j]);
;                 *xp = nv; const float r = bf1(nv); ss[j] += r * r;
;             }
; #pragma unroll
;         for (int j = 0; j < 4; ++j) {
;             float s = ss[j];
;             s += __shfl_xor(s, 1); s += __shfl_xor(s, 2); s += __shfl_xor(s, 4); s += __shfl_xor(s, 8);
;             if (l15 == 0) sspart[(size_t)(r0 + 16 * ra + 4 * g + j) * 32 + cg] = s;
	v_pk_add_f32 v[14:15], v[14:15], v[10:11]
	v_pk_add_f32 v[22:23], v[22:23], v[8:9]
	v_mov_b32_e32 v8, v200
	v_mov_b32_e32 v9, v201
	v_mov_b32_e32 v10, v202
	v_mov_b32_e32 v11, v203
	s_waitcnt lgkmcnt(0)
	v_pk_add_f32 v[14:15], v[14:15], v[10:11]
	v_pk_add_f32 v[22:23], v[22:23], v[8:9]
	v_mov_b32_e32 v8, v204
	v_mov_b32_e32 v9, v205
	v_mov_b32_e32 v10, v206
	v_mov_b32_e32 v11, v207
	s_waitcnt lgkmcnt(0)
	v_pk_add_f32 v[10:11], v[14:15], v[10:11]
	v_pk_add_f32 v[14:15], v[22:23], v[8:9]
	v_pk_add_f32 v[8:9], v[10:11], v[36:37]
	v_add_u32_e32 v10, s27, v31
	v_ashrrev_i32_e32 v11, 31, v10
	v_pk_add_f32 v[22:23], v[14:15], v[34:35]
	v_lshlrev_b64 v[14:15], 12, v[10:11]
	v_lshl_add_u64 v[14:15], v[28:29], 0, v[14:15]
	s_waitcnt vmcnt(0)
	v_mov_b32_e32 v0, v146
	v_lshlrev_b32_e32 v0, 16, v0
	v_add_f32_e32 v0, v20, v0
	v_cvt_pk_bf16_f32 v0, v0, s0
	global_store_short v[14:15], v0, off
	v_lshlrev_b32_e32 v20, 16, v0
	v_mov_b32_e32 v0, v147
	v_lshlrev_b32_e32 v0, 16, v0
	v_add_f32_e32 v0, v26, v0
	v_cvt_pk_bf16_f32 v0, v0, s0
	global_store_short v[14:15], v0, off offset:32
	v_lshlrev_b32_e32 v0, 16, v0
	v_mul_f32_e32 v0, v0, v0
	v_fmac_f32_e32 v0, v20, v20
	v_mov_b32_e32 v20, v148
	v_lshlrev_b32_e32 v20, 16, v20
	v_add_f32_e32 v20, v24, v20
	v_cvt_pk_bf16_f32 v20, v20, s0
	global_store_short v[14:15], v20, off offset:64
	v_lshlrev_b32_e32 v20, 16, v20
	v_fmac_f32_e32 v0, v20, v20
	v_mov_b32_e32 v20, v149
	v_lshlrev_b32_e32 v20, 16, v20
	v_add_f32_e32 v20, v22, v20
	v_cvt_pk_bf16_f32 v20, v20, s0
	global_store_short v[14:15], v20, off offset:96
	v_lshlrev_b32_e32 v14, 16, v20
	v_fmac_f32_e32 v0, v14, v14
	v_or_b32_e32 v14, 1, v10
	v_ashrrev_i32_e32 v15, 31, v14
	v_lshlrev_b64 v[34:35], 12, v[14:15]
	v_lshl_add_u64 v[36:37], v[28:29], 0, v[34:35]
	v_mov_b32_e32 v20, v150
	v_lshlrev_b32_e32 v20, 16, v20
	v_add_f32_e32 v20, v21, v20
	v_cvt_pk_bf16_f32 v26, v20, s0
	v_mov_b32_e32 v20, v151
	v_lshlrev_b32_e32 v20, 16, v20
	v_add_f32_e32 v20, v27, v20
	v_cvt_pk_bf16_f32 v27, v20, s0
	v_mov_b32_e32 v20, v152
	v_lshlrev_b32_e32 v20, 16, v20
	v_add_f32_e32 v20, v25, v20
	v_cvt_pk_bf16_f32 v34, v20, s0
	v_mov_b32_e32 v20, v153
	v_lshlrev_b32_e32 v20, 16, v20
	v_add_f32_e32 v20, v23, v20
	v_cvt_pk_bf16_f32 v35, v20, s0
	v_or_b32_e32 v20, 2, v10
	v_ashrrev_i32_e32 v21, 31, v20
	v_lshlrev_b64 v[22:23], 12, v[20:21]
	v_lshl_add_u64 v[22:23], v[28:29], 0, v[22:23]
	v_mov_b32_e32 v24, v154
	v_lshlrev_b32_e32 v24, 16, v24
	v_add_f32_e32 v12, v12, v24
	v_mov_b32_e32 v24, v155
	v_cvt_pk_bf16_f32 v12, v12, s0
	global_store_short v[22:23], v12, off
	global_store_short v[36:37], v26, off
	global_store_short v[36:37], v27, off offset:32
	global_store_short v[36:37], v34, off offset:64
	global_store_short v[36:37], v35, off offset:96
	v_xor_b32_e32 v36, 8, v215
	s_waitcnt vmcnt(5)
	v_lshlrev_b32_e32 v24, 16, v24
	v_add_f32_e32 v18, v18, v24
	v_mov_b32_e32 v24, v156
	v_cvt_pk_bf16_f32 v18, v18, s0
	global_store_short v[22:23], v18, off offset:32
	s_waitcnt vmcnt(1)
	v_lshlrev_b32_e32 v24, 16, v24
	v_add_f32_e32 v16, v16, v24
	v_mov_b32_e32 v24, v157
	v_cvt_pk_bf16_f32 v16, v16, s0
	global_store_short v[22:23], v16, off offset:64
	s_waitcnt vmcnt(1)
	v_lshlrev_b32_e32 v24, 16, v24
	v_add_f32_e32 v8, v8, v24
	v_cvt_pk_bf16_f32 v8, v8, s0
	global_store_short v[22:23], v8, off offset:96
	v_or_b32_e32 v22, 3, v10
	v_ashrrev_i32_e32 v23, 31, v22
	v_lshlrev_b64 v[24:25], 12, v[22:23]
	v_lshl_add_u64 v[24:25], v[28:29], 0, v[24:25]
	v_mov_b32_e32 v28, v158
	v_lshlrev_b32_e32 v28, 16, v28
	v_add_f32_e32 v13, v13, v28
	v_mov_b32_e32 v28, v159
	v_cvt_pk_bf16_f32 v13, v13, s0
	global_store_short v[24:25], v13, off
	s_waitcnt vmcnt(1)
	v_lshlrev_b32_e32 v28, 16, v28
	v_add_f32_e32 v19, v19, v28
	v_mov_b32_e32 v28, v160
	v_cvt_pk_bf16_f32 v19, v19, s0
	global_store_short v[24:25], v19, off offset:32
	s_waitcnt vmcnt(1)
	v_lshlrev_b32_e32 v28, 16, v28
	v_add_f32_e32 v17, v17, v28
	v_mov_b32_e32 v28, v161
	v_cvt_pk_bf16_f32 v17, v17, s0
	global_store_short v[24:25], v17, off offset:64
	s_waitcnt vmcnt(1)
	v_lshlrev_b32_e32 v28, 16, v28
	v_add_f32_e32 v9, v9, v28
	v_cvt_pk_bf16_f32 v9, v9, s0
	global_store_short v[24:25], v9, off offset:96
	v_and_b32_e32 v25, 64, v215
	v_xor_b32_e32 v24, 1, v215
	v_add_u32_e32 v29, 64, v25
	v_cmp_lt_i32_e32 vcc, v24, v29
	v_xor_b32_e32 v25, 2, v215
	v_xor_b32_e32 v28, 4, v215
	v_cndmask_b32_e32 v24, v215, v24, vcc
	v_cmp_lt_i32_e32 vcc, v25, v29
	v_lshlrev_b32_e32 v24, 2, v24
	s_nop 0
	v_cndmask_b32_e32 v25, v215, v25, vcc
	v_cmp_lt_i32_e32 vcc, v28, v29
	v_lshlrev_b32_e32 v25, 2, v25
	s_nop 0
	v_cndmask_b32_e32 v28, v215, v28, vcc
	v_cmp_lt_i32_e32 vcc, v36, v29
	v_lshlrev_b32_e32 v28, 2, v28
	s_nop 0
	v_cndmask_b32_e32 v29, v215, v36, vcc
	ds_bpermute_b32 v36, v24, v0
	v_lshlrev_b32_e32 v29, 2, v29
	s_waitcnt lgkmcnt(0)
	v_add_f32_e32 v0, v0, v36
	ds_bpermute_b32 v36, v25, v0
	s_waitcnt lgkmcnt(0)
	v_add_f32_e32 v0, v0, v36
	ds_bpermute_b32 v36, v28, v0
	s_waitcnt lgkmcnt(0)
	v_add_f32_e32 v0, v0, v36
	ds_bpermute_b32 v36, v29, v0
	s_and_saveexec_b64 s[26:27], s[8:9]
	s_cbranch_execz .LBB0_545
	v_lshlrev_b64 v[10:11], 7, v[10:11]
	v_lshl_add_u64 v[10:11], s[12:13], 0, v[10:11]
	s_waitcnt lgkmcnt(0)
	v_add_f32_e32 v0, v0, v36
	global_store_dword v[10:11], v0, off

; #define LAS __attribute__((address_space(3)))
; #define MFMA16(a, b, c) __builtin_amdgcn_mfma_f32_16x16x32_bf16((a), (b), (c), 0, 0, 0)
; __device__ __forceinline__ void sample_out_block(LAS unsigned char* lds, const bf16_t* A, const bf16_t* Bt, int K, bf16_t* xb, float* sspart, int blk, int tid) {
;     const int wave = tid >> 6, lane = tid & 63, l15 = lane & 15, g = lane >> 4;
;     const int rt = blk >> 5, cg = blk & 31, r0 = T_P + 32 * rt;
;     const int kq = K >> 3;
;     f32x4 acc[2][4];
; #pragma unroll
;     for (int ra = 0; ra < 2; ++ra)
; #pragma unroll
;         for (int nt = 0; nt < 4; ++nt) acc[ra][nt] = (f32x4){0.f, 0.f, 0.f, 0.f};
;     {
;         const bf16_t* ap = A + (size_t)(r0 + l15) * K + wave * kq + 8 * g;
;         const bf16_t* bp = Bt + (size_t)(64 * cg + l15) * K + wave * kq + 8 * g;
;         bf16x8 af[2][2], bf[2][4], afn[2][2], bfn[2][4];
; #pragma unroll
;         for (int s = 0; s < 2; ++s) {
; #pragma unroll
;             for (int ra = 0; ra < 2; ++ra) af[s][ra] = *(const bf16x8*)(ap + (size_t)(16 * ra) * K + 32 * s);
; #pragma unroll
;             for (int nt = 0; nt < 4; ++nt) bf[s][nt] = *(const bf16x8*)(bp + (size_t)(16 * nt) * K + 32 * s);
;         }
;         for (int k0 = 0; k0 < kq; k0 += 64) {
;             const int k1 = (k0 + 64 < kq) ? k0 + 64 : k0;
; #pragma unroll
;             for (int s = 0; s < 2; ++s) {
; #pragma unroll
;                 for (int ra = 0; ra < 2; ++ra) afn[s][ra] = *(const bf16x8*)(ap + (size_t)(16 * ra) * K + k1 + 32 * s);
; #pragma unroll
;                 for (int nt = 0; nt < 4; ++nt) bfn[s][nt] = *(const bf16x8*)(bp + (size_t)(16 * nt) * K + k1 + 32 * s);
;             }
; #pragma unroll
;             for (int s = 0; s < 2; ++s)
; #pragma unroll
;                 for (int ra = 0; ra < 2; ++ra)
; #pragma unroll
;                     for (int nt = 0; nt < 4; ++nt) acc[ra][nt] = MFMA16(af[s][ra], bf[s][nt], acc[ra][nt]);
.LBB0_1165:
	s_and_b32 s21, s26, 0xffffffe0
	s_addk_i32 s21, 0x2000
	s_and_b32 s20, s26, 31
	v_or_b32_e32 v8, s21, v30
	v_ashrrev_i32_e32 v9, 31, v8
	s_lshl_b32 s27, s20, 6
	v_lshlrev_b64 v[8:9], 12, v[8:9]
	v_or_b32_e32 v0, s27, v30
	v_lshl_add_u64 v[10:11], v[2:3], 0, v[8:9]
	v_lshlrev_b32_e32 v0, 12, v0
	v_lshl_add_u64 v[16:17], v[4:5], 0, v[0:1]
	v_add_co_u32_e32 v8, vcc, 0x10000, v10
	s_mov_b64 s[8:9], vcc
	v_add_co_u32_e32 v12, vcc, 0x10000, v16
	v_readfirstlane_b32 s36, v139
	s_lshr_b32 s36, s36, 6
	s_and_b32 s37, s26, 0xffffffe0
	s_addk_i32 s37, 0x2000
	s_and_b32 s38, s26, 31
	s_lshl_b32 s38, s38, 6
	s_lshl_b32 s39, s37, 12
	s_mul_i32 s40, s36, 0x200
	s_add_u32 s42, s18, s39
	s_addc_u32 s43, s19, 0
	s_add_u32 s42, s42, s40
	s_addc_u32 s43, s43, 0
	s_lshl_b32 s41, s24, 1
	s_lshl_b32 s39, s38, 12
	s_add_u32 s44, s22, s41
	s_addc_u32 s45, s23, 0
	s_add_u32 s44, s44, s39
	s_addc_u32 s45, s45, 0
	s_add_u32 s44, s44, s40
	s_addc_u32 s45, s45, 0
	v_lshrrev_b32_e32 v227, 3, v215
	v_and_b32_e32 v228, 7, v215
	v_lshlrev_b32_e32 v198, 12, v227
	v_lshl_add_u32 v198, v228, 4, v198
	v_add_u32_e32 v199, 0x8000, v198
	v_add_u32_e32 v200, 0x10000, v198
	v_add_u32_e32 v201, 0x18000, v198
	v_add_u32_e32 v202, 0x20000, v198
	v_add_u32_e32 v203, 0x28000, v198
	v_add_u32_e32 v204, 0x30000, v198
	v_add_u32_e32 v205, 0x38000, v198
	s_lshl_b32 s46, s36, 13
	s_mul_i32 s47, s36, 0x1800
	s_add_i32 s47, s47, 0x10000
	v_mul_u32_u24_e32 v206, 0x90, v227
	v_lshl_add_u32 v206, v228, 4, v206
	v_add_u32_e32 v207, s47, v206
	v_add_u32_e32 v206, s46, v206
	v_and_b32_e32 v227, 15, v215
	v_lshrrev_b32_e32 v228, 4, v215
	v_mul_u32_u24_e32 v208, 0x90, v227
	v_lshl_add_u32 v208, v228, 4, v208
	v_add_u32_e32 v209, s47, v208
	v_add_u32_e32 v208, s46, v208
	v_add_u32_e32 v226, 0x1b00, v208
	v_subrev_u32_e32 v228, 0x480, v209
	v_cmp_gt_u32_e32 vcc, 8, v227
	v_cndmask_b32_e32 v226, v228, v226, vcc
	global_load_dwordx4 v[34:37], v198, s[42:43]
	global_load_dwordx4 v[38:41], v199, s[42:43]
	global_load_dwordx4 v[42:45], v200, s[42:43]
	global_load_dwordx4 v[46:49], v201, s[42:43]
	global_load_dwordx4 v[50:53], v198, s[44:45]
	global_load_dwordx4 v[54:57], v199, s[44:45]
	global_load_dwordx4 v[58:61], v200, s[44:45]
	global_load_dwordx4 v[62:65], v201, s[44:45]
	global_load_dwordx4 v[66:69], v202, s[44:45]
	global_load_dwordx4 v[70:73], v203, s[44:45]
	global_load_dwordx4 v[74:77], v204, s[44:45]
	global_load_dwordx4 v[78:81], v205, s[44:45]
	global_load_dwordx4 v[82:85], v198, s[42:43] offset:128
	global_load_dwordx4 v[86:89], v199, s[42:43] offset:128
	global_load_dwordx4 v[90:93], v200, s[42:43] offset:128
	global_load_dwordx4 v[94:97], v201, s[42:43] offset:128
	global_load_dwordx4 v[98:101], v198, s[44:45] offset:128
	global_load_dwordx4 v[102:105], v199, s[44:45] offset:128
	global_load_dwordx4 v[106:109], v200, s[44:45] offset:128
	global_load_dwordx4 v[110:113], v201, s[44:45] offset:128
	global_load_dwordx4 v[114:117], v202, s[44:45] offset:128
	global_load_dwordx4 v[118:121], v203, s[44:45] offset:128
	global_load_dwordx4 v[122:125], v204, s[44:45] offset:128
	global_load_dwordx4 v[126:129], v205, s[44:45] offset:128
	s_waitcnt vmcnt(12)
	ds_write_b128 v206, v[34:37]
	ds_write_b128 v206, v[38:41] offset:1152
	ds_write_b128 v206, v[42:45] offset:2304
	ds_write_b128 v206, v[46:49] offset:3456
	ds_write_b128 v206, v[50:53] offset:4608
	ds_write_b128 v206, v[54:57] offset:5760
	ds_write_b128 v206, v[58:61] offset:6912
	ds_write_b128 v207, v[62:65]
	ds_write_b128 v207, v[66:69] offset:1152
	ds_write_b128 v207, v[70:73] offset:2304
	ds_write_b128 v207, v[74:77] offset:3456
	ds_write_b128 v207, v[78:81] offset:4608
	global_load_dwordx4 v[34:37], v198, s[42:43] offset:256
	global_load_dwordx4 v[38:41], v199, s[42:43] offset:256
	global_load_dwordx4 v[42:45], v200, s[42:43] offset:256
	global_load_dwordx4 v[46:49], v201, s[42:43] offset:256
	global_load_dwordx4 v[50:53], v198, s[44:45] offset:256
	global_load_dwordx4 v[54:57], v199, s[44:45] offset:256
	global_load_dwordx4 v[58:61], v200, s[44:45] offset:256
	global_load_dwordx4 v[62:65], v201, s[44:45] offset:256
	global_load_dwordx4 v[66:69], v202, s[44:45] offset:256
	global_load_dwordx4 v[70:73], v203, s[44:45] offset:256
	global_load_dwordx4 v[74:77], v204, s[44:45] offset:256
	global_load_dwordx4 v[78:81], v205, s[44:45] offset:256
	ds_read_b128 v[146:149], v208 offset:0
	ds_read_b128 v[150:153], v208 offset:2304
	ds_read_b128 v[154:157], v208 offset:4608
	ds_read_b128 v[158:161], v226
	ds_read_b128 v[162:165], v209 offset:1152
	ds_read_b128 v[166:169], v209 offset:3456
	ds_read_b128 v[170:173], v208 offset:64
	ds_read_b128 v[174:177], v208 offset:2368
	ds_read_b128 v[178:181], v208 offset:4672
	ds_read_b128 v[182:185], v226 offset:64
	ds_read_b128 v[186:189], v209 offset:1216
	ds_read_b128 v[190:193], v209 offset:3520
	s_waitcnt lgkmcnt(6)
	v_mfma_f32_16x16x32_bf16 v[8:11], v[146:149], v[154:157], 0
	v_mfma_f32_16x16x32_bf16 v[12:15], v[146:149], v[158:161], 0
	v_mfma_f32_16x16x32_bf16 v[16:19], v[146:149], v[162:165], 0
	v_mfma_f32_16x16x32_bf16 v[20:23], v[146:149], v[166:169], 0
	v_mfma_f32_16x16x32_bf16 v[24:27], v[150:153], v[154:157], 0
	v_mfma_f32_16x16x32_bf16 v[130:133], v[150:153], v[158:161], 0
	v_mfma_f32_16x16x32_bf16 v[134:137], v[150:153], v[162:165], 0
	v_mfma_f32_16x16x32_bf16 v[194:197], v[150:153], v[166:169], 0
	s_waitcnt lgkmcnt(0)
; #define MFMA16(a, b, c) __builtin_amdgcn_mfma_f32_16x16x32_bf16((a), (b), (c), 0, 0, 0)
; __device__ __forceinline__ void sample_out_block(LAS unsigned char* lds, const bf16_t* A, const bf16_t* Bt, int K, bf16_t* xb, float* sspart, int blk, int tid) {
;     ...
;         for (int k0 = 0; k0 < kq; k0 += 64) {
;             const int k1 = (k0 + 64 < kq) ? k0 + 64 : k0;
; #pragma unroll
;             for (int s = 0; s < 2; ++s) {
; #pragma unroll
;                 for (int ra = 0; ra < 2; ++ra) afn[s][ra] = *(const bf16x8*)(ap + (size_t)(16 * ra) * K + k1 + 32 * s);
; #pragma unroll
;                 for (int nt = 0; nt < 4; ++nt) bfn[s][nt] = *(const bf16x8*)(bp + (size_t)(16 * nt) * K + k1 + 32 * s);
;             }
; #pragma unroll
;             for (int s = 0; s < 2; ++s)
; #pragma unroll
;                 for (int ra = 0; ra < 2; ++ra)
; #pragma unroll
;                     for (int nt = 0; nt < 4; ++nt) acc[ra][nt] = MFMA16(af[s][ra], bf[s][nt], acc[ra][nt]);
; #pragma unroll
;             for (int s = 0; s < 2; ++s) {
; #pragma unroll
;                 for (int ra = 0; ra < 2; ++ra) af[s][ra] = afn[s][ra];
; #pragma unroll
;                 for (int nt = 0; nt < 4; ++nt) bf[s][nt] = bfn[s][nt];
;             }
;         }
	v_mfma_f32_16x16x32_bf16 v[8:11], v[170:173], v[178:181], v[8:11]
	v_mfma_f32_16x16x32_bf16 v[12:15], v[170:173], v[182:185], v[12:15]
	v_mfma_f32_16x16x32_bf16 v[16:19], v[170:173], v[186:189], v[16:19]
	v_mfma_f32_16x16x32_bf16 v[20:23], v[170:173], v[190:193], v[20:23]
	v_mfma_f32_16x16x32_bf16 v[24:27], v[174:177], v[178:181], v[24:27]
	v_mfma_f32_16x16x32_bf16 v[130:133], v[174:177], v[182:185], v[130:133]
	v_mfma_f32_16x16x32_bf16 v[134:137], v[174:177], v[186:189], v[134:137]
	v_mfma_f32_16x16x32_bf16 v[194:197], v[174:177], v[190:193], v[194:197]
	s_waitcnt vmcnt(12)
	ds_write_b128 v206, v[82:85]
	ds_write_b128 v206, v[86:89] offset:1152
	ds_write_b128 v206, v[90:93] offset:2304
	ds_write_b128 v206, v[94:97] offset:3456
	ds_write_b128 v206, v[98:101] offset:4608
	ds_write_b128 v206, v[102:105] offset:5760
	ds_write_b128 v206, v[106:109] offset:6912
	ds_write_b128 v207, v[110:113]
	ds_write_b128 v207, v[114:117] offset:1152
	ds_write_b128 v207, v[118:121] offset:2304
	ds_write_b128 v207, v[122:125] offset:3456
	ds_write_b128 v207, v[126:129] offset:4608
	global_load_dwordx4 v[82:85], v198, s[42:43] offset:384
	global_load_dwordx4 v[86:89], v199, s[42:43] offset:384
	global_load_dwordx4 v[90:93], v200, s[42:43] offset:384
	global_load_dwordx4 v[94:97], v201, s[42:43] offset:384
	global_load_dwordx4 v[98:101], v198, s[44:45] offset:384
	global_load_dwordx4 v[102:105], v199, s[44:45] offset:384
	global_load_dwordx4 v[106:109], v200, s[44:45] offset:384
	global_load_dwordx4 v[110:113], v201, s[44:45] offset:384
	global_load_dwordx4 v[114:117], v202, s[44:45] offset:384
	global_load_dwordx4 v[118:121], v203, s[44:45] offset:384
	global_load_dwordx4 v[122:125], v204, s[44:45] offset:384
	global_load_dwordx4 v[126:129], v205, s[44:45] offset:384
	ds_read_b128 v[146:149], v208 offset:0
	ds_read_b128 v[150:153], v208 offset:2304
	ds_read_b128 v[154:157], v208 offset:4608
	ds_read_b128 v[158:161], v226
	ds_read_b128 v[162:165], v209 offset:1152
	ds_read_b128 v[166:169], v209 offset:3456
	ds_read_b128 v[170:173], v208 offset:64
	ds_read_b128 v[174:177], v208 offset:2368
	ds_read_b128 v[178:181], v208 offset:4672
	ds_read_b128 v[182:185], v226 offset:64
	ds_read_b128 v[186:189], v209 offset:1216
	ds_read_b128 v[190:193], v209 offset:3520
	s_waitcnt lgkmcnt(6)
	v_mfma_f32_16x16x32_bf16 v[8:11], v[146:149], v[154:157], v[8:11]
	v_mfma_f32_16x16x32_bf16 v[12:15], v[146:149], v[158:161], v[12:15]
	v_mfma_f32_16x16x32_bf16 v[16:19], v[146:149], v[162:165], v[16:19]
	v_mfma_f32_16x16x32_bf16 v[20:23], v[146:149], v[166:169], v[20:23]
	v_mfma_f32_16x16x32_bf16 v[24:27], v[150:153], v[154:157], v[24:27]
	v_mfma_f32_16x16x32_bf16 v[130:133], v[150:153], v[158:161], v[130:133]
	v_mfma_f32_16x16x32_bf16 v[134:137], v[150:153], v[162:165], v[134:137]
	v_mfma_f32_16x16x32_bf16 v[194:197], v[150:153], v[166:169], v[194:197]
	s_waitcnt lgkmcnt(0)
	v_mfma_f32_16x16x32_bf16 v[8:11], v[170:173], v[178:181], v[8:11]
	v_mfma_f32_16x16x32_bf16 v[12:15], v[170:173], v[182:185], v[12:15]
	v_mfma_f32_16x16x32_bf16 v[16:19], v[170:173], v[186:189], v[16:19]
	v_mfma_f32_16x16x32_bf16 v[20:23], v[170:173], v[190:193], v[20:23]
	v_mfma_f32_16x16x32_bf16 v[24:27], v[174:177], v[178:181], v[24:27]
	v_mfma_f32_16x16x32_bf16 v[130:133], v[174:177], v[182:185], v[130:133]
	v_mfma_f32_16x16x32_bf16 v[134:137], v[174:177], v[186:189], v[134:137]
	v_mfma_f32_16x16x32_bf16 v[194:197], v[174:177], v[190:193], v[194:197]
	s_waitcnt vmcnt(12)
	ds_write_b128 v206, v[34:37]
	ds_write_b128 v206, v[38:41] offset:1152
	ds_write_b128 v206, v[42:45] offset:2304
	ds_write_b128 v206, v[46:49] offset:3456
	ds_write_b128 v206, v[50:53] offset:4608
	ds_write_b128 v206, v[54:57] offset:5760
	ds_write_b128 v206, v[58:61] offset:6912
	ds_write_b128 v207, v[62:65]
	ds_write_b128 v207, v[66:69] offset:1152
	ds_write_b128 v207, v[70:73] offset:2304
	ds_write_b128 v207, v[74:77] offset:3456
	ds_write_b128 v207, v[78:81] offset:4608
	ds_read_b128 v[146:149], v208 offset:0
	ds_read_b128 v[150:153], v208 offset:2304
	ds_read_b128 v[154:157], v208 offset:4608
	ds_read_b128 v[158:161], v226
	ds_read_b128 v[162:165], v209 offset:1152
	ds_read_b128 v[166:169], v209 offset:3456
	ds_read_b128 v[170:173], v208 offset:64
	ds_read_b128 v[174:177], v208 offset:2368
	ds_read_b128 v[178:181], v208 offset:4672
	ds_read_b128 v[182:185], v226 offset:64
	ds_read_b128 v[186:189], v209 offset:1216
	ds_read_b128 v[190:193], v209 offset:3520
	s_waitcnt lgkmcnt(6)
	v_mfma_f32_16x16x32_bf16 v[8:11], v[146:149], v[154:157], v[8:11]
	v_mfma_f32_16x16x32_bf16 v[12:15], v[146:149], v[158:161], v[12:15]
	v_mfma_f32_16x16x32_bf16 v[16:19], v[146:149], v[162:165], v[16:19]
	v_mfma_f32_16x16x32_bf16 v[20:23], v[146:149], v[166:169], v[20:23]
	v_mfma_f32_16x16x32_bf16 v[24:27], v[150:153], v[154:157], v[24:27]
	v_mfma_f32_16x16x32_bf16 v[130:133], v[150:153], v[158:161], v[130:133]
	v_mfma_f32_16x16x32_bf16 v[134:137], v[150:153], v[162:165], v[134:137]
	v_mfma_f32_16x16x32_bf16 v[194:197], v[150:153], v[166:169], v[194:197]
	s_waitcnt lgkmcnt(0)
	v_mfma_f32_16x16x32_bf16 v[8:11], v[170:173], v[178:181], v[8:11]
	v_mfma_f32_16x16x32_bf16 v[12:15], v[170:173], v[182:185], v[12:15]
	v_mfma_f32_16x16x32_bf16 v[16:19], v[170:173], v[186:189], v[16:19]
	v_mfma_f32_16x16x32_bf16 v[20:23], v[170:173], v[190:193], v[20:23]
	v_mfma_f32_16x16x32_bf16 v[24:27], v[174:177], v[178:181], v[24:27]
	v_mfma_f32_16x16x32_bf16 v[130:133], v[174:177], v[182:185], v[130:133]
	v_mfma_f32_16x16x32_bf16 v[134:137], v[174:177], v[186:189], v[134:137]
	v_mfma_f32_16x16x32_bf16 v[194:197], v[174:177], v[190:193], v[194:197]
	s_waitcnt vmcnt(0)
; #define LAS __attribute__((address_space(3)))
; __device__ __forceinline__ float bf1(bf16_t h) { return __uint_as_float((unsigned)h << 16); }
; __device__ __forceinline__ bf16_t f2bf(float f) { return (bf16_t)(pk2(f, 0.f) & 0xffffu); }
; __device__ __forceinline__ void sample_out_block(LAS unsigned char* lds, const bf16_t* A, const bf16_t* Bt, int K, bf16_t* xb, float* sspart, int blk, int tid) {
;     ...
;     LAS f32x4* part = (LAS f32x4*)lds;
; #pragma unroll
;     for (int ra = 0; ra < 2; ++ra)
; #pragma unroll
;         for (int nt = 0; nt < 4; ++nt) part[(wave * 8 + ra * 4 + nt) * 64 + lane] = acc[ra][nt];
;     __syncthreads();
;     if (wave < 2) {
;         const int ra = wave;
;         f32x4 sum[4];
; #pragma unroll
;         for (int nt = 0; nt < 4; ++nt) {
;             sum[nt] = part[(0 * 8 + ra * 4 + nt) * 64 + lane];
; #pragma unroll
;             for (int w = 1; w < 8; ++w) sum[nt] += part[(w * 8 + ra * 4 + nt) * 64 + lane];
;         }
;         float ss[4] = {0.f, 0.f, 0.f, 0.f};
; #pragma unroll
;         for (int j = 0; j < 4; ++j)
; #pragma unroll
;             for (int nt = 0; nt < 4; ++nt) {
;                 bf16_t* xp = xb + (size_t)(r0 + 16 * ra + 4 * g + j) * 2048 + 64 * cg + 16 * nt + l15;
;                 const bf16_t nv = f2bf(bf1(*xp) + sum[nt][j]);
	ds_write_b128 v206, v[82:85]
	ds_write_b128 v206, v[86:89] offset:1152
	ds_write_b128 v206, v[90:93] offset:2304
	ds_write_b128 v206, v[94:97] offset:3456
	ds_write_b128 v206, v[98:101] offset:4608
	ds_write_b128 v206, v[102:105] offset:5760
	ds_write_b128 v206, v[106:109] offset:6912
	ds_write_b128 v207, v[110:113]
	ds_write_b128 v207, v[114:117] offset:1152
	ds_write_b128 v207, v[118:121] offset:2304
	ds_write_b128 v207, v[122:125] offset:3456
	ds_write_b128 v207, v[126:129] offset:4608
	ds_read_b128 v[146:149], v208 offset:0
	ds_read_b128 v[150:153], v208 offset:2304
	ds_read_b128 v[154:157], v208 offset:4608
	ds_read_b128 v[158:161], v226
	ds_read_b128 v[162:165], v209 offset:1152
	ds_read_b128 v[166:169], v209 offset:3456
	ds_read_b128 v[170:173], v208 offset:64
	ds_read_b128 v[174:177], v208 offset:2368
	ds_read_b128 v[178:181], v208 offset:4672
	ds_read_b128 v[182:185], v226 offset:64
	ds_read_b128 v[186:189], v209 offset:1216
	ds_read_b128 v[190:193], v209 offset:3520
	s_waitcnt lgkmcnt(6)
	v_mfma_f32_16x16x32_bf16 v[8:11], v[146:149], v[154:157], v[8:11]
	v_mfma_f32_16x16x32_bf16 v[12:15], v[146:149], v[158:161], v[12:15]
	v_mfma_f32_16x16x32_bf16 v[16:19], v[146:149], v[162:165], v[16:19]
	v_mfma_f32_16x16x32_bf16 v[20:23], v[146:149], v[166:169], v[20:23]
	v_mfma_f32_16x16x32_bf16 v[24:27], v[150:153], v[154:157], v[24:27]
	v_mfma_f32_16x16x32_bf16 v[130:133], v[150:153], v[158:161], v[130:133]
	v_mfma_f32_16x16x32_bf16 v[134:137], v[150:153], v[162:165], v[134:137]
	v_mfma_f32_16x16x32_bf16 v[194:197], v[150:153], v[166:169], v[194:197]
	s_waitcnt lgkmcnt(0)
	v_mfma_f32_16x16x32_bf16 v[8:11], v[170:173], v[178:181], v[8:11]
	v_mfma_f32_16x16x32_bf16 v[12:15], v[170:173], v[182:185], v[12:15]
	v_mfma_f32_16x16x32_bf16 v[16:19], v[170:173], v[186:189], v[16:19]
	v_mfma_f32_16x16x32_bf16 v[20:23], v[170:173], v[190:193], v[20:23]
	v_mfma_f32_16x16x32_bf16 v[24:27], v[174:177], v[178:181], v[24:27]
	v_mfma_f32_16x16x32_bf16 v[130:133], v[174:177], v[182:185], v[130:133]
	v_mfma_f32_16x16x32_bf16 v[134:137], v[174:177], v[186:189], v[134:137]
	v_mfma_f32_16x16x32_bf16 v[194:197], v[174:177], v[190:193], v[194:197]
	s_nop 7
	s_nop 7
	ds_write_b128 v32, v[8:11]
	ds_write_b128 v32, v[12:15] offset:1024
	ds_write_b128 v32, v[16:19] offset:2048
	ds_write_b128 v32, v[20:23] offset:3072
	ds_write_b128 v32, v[24:27] offset:4096
	ds_write_b128 v32, v[130:133] offset:5120
	ds_write_b128 v32, v[134:137] offset:6144
	ds_write_b128 v32, v[194:197] offset:7168
	s_waitcnt lgkmcnt(0)
	s_barrier
	s_and_saveexec_b64 s[8:9], s[4:5]
	s_cbranch_execz .LBB0_1164
	v_add_u32_e32 v170, s21, v31
	v_lshlrev_b32_e32 v170, 12, v170
	s_lshl_b32 s36, s27, 1
	v_add_u32_e32 v170, s36, v170
	v_mov_b32_e32 v171, 0
	s_mov_b64 s[38:39], 0x1000
	v_lshl_add_u64 v[162:163], v[6:7], 0, v[170:171]
	v_lshl_add_u64 v[164:165], v[162:163], 0, s[38:39]
	v_lshl_add_u64 v[166:167], v[164:165], 0, s[38:39]
	v_lshl_add_u64 v[168:169], v[166:167], 0, s[38:39]
	global_load_ushort v146, v[162:163], off
	global_load_ushort v147, v[162:163], off offset:32
	global_load_ushort v148, v[162:163], off offset:64
	global_load_ushort v149, v[162:163], off offset:96
	global_load_ushort v150, v[164:165], off
	global_load_ushort v151, v[164:165], off offset:32
	global_load_ushort v152, v[164:165], off offset:64
	global_load_ushort v153, v[164:165], off offset:96
	global_load_ushort v154, v[166:167], off
	global_load_ushort v155, v[166:167], off offset:32
	global_load_ushort v156, v[166:167], off offset:64
	global_load_ushort v157, v[166:167], off offset:96
	global_load_ushort v158, v[168:169], off
	global_load_ushort v159, v[168:169], off offset:32
	global_load_ushort v160, v[168:169], off offset:64
	global_load_ushort v161, v[168:169], off offset:96
	ds_read_b128 v[38:41], v33
	ds_read_b128 v[42:45], v33 offset:8192
	ds_read_b128 v[46:49], v33 offset:16384
	ds_read_b128 v[50:53], v33 offset:24576
	ds_read_b128 v[54:57], v33 offset:32768
	ds_read_b128 v[58:61], v33 offset:40960
	ds_read_b128 v[62:65], v33 offset:49152
	ds_read_b128 v[66:69], v33 offset:57344
	ds_read_b128 v[70:73], v33 offset:1024
	ds_read_b128 v[74:77], v33 offset:9216
	ds_read_b128 v[78:81], v33 offset:17408
	ds_read_b128 v[82:85], v33 offset:25600
	ds_read_b128 v[86:89], v33 offset:33792
	ds_read_b128 v[90:93], v33 offset:41984
	ds_read_b128 v[94:97], v33 offset:50176
	ds_read_b128 v[98:101], v33 offset:58368
	ds_read_b128 v[102:105], v33 offset:2048
	ds_read_b128 v[106:109], v33 offset:10240
	ds_read_b128 v[110:113], v33 offset:18432
	ds_read_b128 v[114:117], v33 offset:26624
	ds_read_b128 v[118:121], v33 offset:34816
	ds_read_b128 v[122:125], v33 offset:43008
	ds_read_b128 v[126:129], v33 offset:51200
	ds_read_b128 v[172:175], v33 offset:59392
	ds_read_b128 v[176:179], v33 offset:3072
	ds_read_b128 v[180:183], v33 offset:11264
	ds_read_b128 v[184:187], v33 offset:19456
	ds_read_b128 v[188:191], v33 offset:60416
	ds_read_b128 v[192:195], v33 offset:27648
	ds_read_b128 v[196:199], v33 offset:35840
	ds_read_b128 v[200:203], v33 offset:44032
	ds_read_b128 v[204:207], v33 offset:52224
	s_waitcnt lgkmcnt(0)
	v_mov_b32_e32 v8, v38
	v_mov_b32_e32 v9, v39
	v_mov_b32_e32 v10, v40
	v_mov_b32_e32 v11, v41
	v_mov_b32_e32 v12, v42
	v_mov_b32_e32 v13, v43
	v_mov_b32_e32 v14, v44
	v_mov_b32_e32 v15, v45
	s_lshl_b32 s80, s27, 1
	v_lshl_add_u64 v[28:29], v[6:7], 0, s[80:81]
	s_lshl_b32 s10, s20, 2
	s_add_u32 s10, s16, s10
	s_waitcnt lgkmcnt(0)
	v_pk_add_f32 v[14:15], v[10:11], v[14:15]
	v_pk_add_f32 v[12:13], v[8:9], v[12:13]
	v_mov_b32_e32 v8, v46
	v_mov_b32_e32 v9, v47
	v_mov_b32_e32 v10, v48
	v_mov_b32_e32 v11, v49
	s_addc_u32 s11, s17, 0
	s_waitcnt lgkmcnt(0)
; __device__ __forceinline__ void sample_out_block(LAS unsigned char* lds, const bf16_t* A, const bf16_t* Bt, int K, bf16_t* xb, float* sspart, int blk, int tid) {
;     ...
;         for (int nt = 0; nt < 4; ++nt) {
;             sum[nt] = part[(0 * 8 + ra * 4 + nt) * 64 + lane];
; #pragma unroll
;             for (int w = 1; w < 8; ++w) sum[nt] += part[(w * 8 + ra * 4 + nt) * 64 + lane];
;         }
	v_pk_add_f32 v[14:15], v[14:15], v[10:11]
	v_pk_add_f32 v[12:13], v[12:13], v[8:9]
	v_mov_b32_e32 v8, v50
	v_mov_b32_e32 v9, v51
	v_mov_b32_e32 v10, v52
	v_mov_b32_e32 v11, v53
	s_waitcnt lgkmcnt(0)
	v_pk_add_f32 v[14:15], v[14:15], v[10:11]
	v_pk_add_f32 v[12:13], v[12:13], v[8:9]
	v_mov_b32_e32 v8, v54
	v_mov_b32_e32 v9, v55
	v_mov_b32_e32 v10, v56
	v_mov_b32_e32 v11, v57
	s_waitcnt lgkmcnt(0)
	v_pk_add_f32 v[14:15], v[14:15], v[10:11]
	v_pk_add_f32 v[12:13], v[12:13], v[8:9]
	v_mov_b32_e32 v8, v58
	v_mov_b32_e32 v9, v59
	v_mov_b32_e32 v10, v60
	v_mov_b32_e32 v11, v61
	s_waitcnt lgkmcnt(0)
	v_pk_add_f32 v[14:15], v[14:15], v[10:11]
	v_pk_add_f32 v[12:13], v[12:13], v[8:9]
	v_mov_b32_e32 v8, v62
	v_mov_b32_e32 v9, v63
	v_mov_b32_e32 v10, v64
	v_mov_b32_e32 v11, v65
	s_waitcnt lgkmcnt(0)
	v_pk_add_f32 v[14:15], v[14:15], v[10:11]
	v_pk_add_f32 v[16:17], v[12:13], v[8:9]
	v_mov_b32_e32 v8, v66
	v_mov_b32_e32 v9, v67
	v_mov_b32_e32 v10, v68
	v_mov_b32_e32 v11, v69
	s_waitcnt lgkmcnt(0)
	v_pk_add_f32 v[12:13], v[14:15], v[10:11]
	v_pk_add_f32 v[20:21], v[16:17], v[8:9]
	v_mov_b32_e32 v8, v70
	v_mov_b32_e32 v9, v71
	v_mov_b32_e32 v10, v72
	v_mov_b32_e32 v11, v73
	v_mov_b32_e32 v14, v74
	v_mov_b32_e32 v15, v75
	v_mov_b32_e32 v16, v76
	v_mov_b32_e32 v17, v77
	s_waitcnt lgkmcnt(0)
	v_pk_add_f32 v[16:17], v[10:11], v[16:17]
	v_pk_add_f32 v[14:15], v[8:9], v[14:15]
	v_mov_b32_e32 v8, v78
	v_mov_b32_e32 v9, v79
	v_mov_b32_e32 v10, v80
	v_mov_b32_e32 v11, v81
	s_waitcnt lgkmcnt(0)
	v_pk_add_f32 v[16:17], v[16:17], v[10:11]
	v_pk_add_f32 v[14:15], v[14:15], v[8:9]
	v_mov_b32_e32 v8, v82
	v_mov_b32_e32 v9, v83
	v_mov_b32_e32 v10, v84
	v_mov_b32_e32 v11, v85
	s_waitcnt lgkmcnt(0)
	v_pk_add_f32 v[16:17], v[16:17], v[10:11]
	v_pk_add_f32 v[14:15], v[14:15], v[8:9]
	v_mov_b32_e32 v8, v86
	v_mov_b32_e32 v9, v87
	v_mov_b32_e32 v10, v88
	v_mov_b32_e32 v11, v89
	s_waitcnt lgkmcnt(0)
	v_pk_add_f32 v[16:17], v[16:17], v[10:11]
	v_pk_add_f32 v[14:15], v[14:15], v[8:9]
	v_mov_b32_e32 v8, v90
	v_mov_b32_e32 v9, v91
	v_mov_b32_e32 v10, v92
	v_mov_b32_e32 v11, v93
	s_waitcnt lgkmcnt(0)
	v_pk_add_f32 v[16:17], v[16:17], v[10:11]
	v_pk_add_f32 v[14:15], v[14:15], v[8:9]
	v_mov_b32_e32 v8, v94
	v_mov_b32_e32 v9, v95
	v_mov_b32_e32 v10, v96
	v_mov_b32_e32 v11, v97
	s_waitcnt lgkmcnt(0)
	v_pk_add_f32 v[16:17], v[16:17], v[10:11]
	v_pk_add_f32 v[14:15], v[14:15], v[8:9]
	v_mov_b32_e32 v8, v98
	v_mov_b32_e32 v9, v99
	v_mov_b32_e32 v10, v100
	v_mov_b32_e32 v11, v101
	s_waitcnt lgkmcnt(0)
	v_pk_add_f32 v[18:19], v[16:17], v[10:11]
	v_pk_add_f32 v[26:27], v[14:15], v[8:9]
	v_mov_b32_e32 v8, v102
	v_mov_b32_e32 v9, v103
	v_mov_b32_e32 v10, v104
	v_mov_b32_e32 v11, v105
	v_mov_b32_e32 v14, v106
	v_mov_b32_e32 v15, v107
	v_mov_b32_e32 v16, v108
	v_mov_b32_e32 v17, v109
	s_waitcnt lgkmcnt(0)
	v_pk_add_f32 v[16:17], v[10:11], v[16:17]
	v_pk_add_f32 v[14:15], v[8:9], v[14:15]
	v_mov_b32_e32 v8, v110
	v_mov_b32_e32 v9, v111
	v_mov_b32_e32 v10, v112
	v_mov_b32_e32 v11, v113
	s_waitcnt lgkmcnt(0)
	v_pk_add_f32 v[16:17], v[16:17], v[10:11]
	v_pk_add_f32 v[14:15], v[14:15], v[8:9]
	v_mov_b32_e32 v8, v114
	v_mov_b32_e32 v9, v115
	v_mov_b32_e32 v10, v116
	v_mov_b32_e32 v11, v117
	s_waitcnt lgkmcnt(0)
	v_pk_add_f32 v[16:17], v[16:17], v[10:11]
	v_pk_add_f32 v[14:15], v[14:15], v[8:9]
	v_mov_b32_e32 v8, v118
	v_mov_b32_e32 v9, v119
	v_mov_b32_e32 v10, v120
	v_mov_b32_e32 v11, v121
	s_waitcnt lgkmcnt(0)
	v_pk_add_f32 v[16:17], v[16:17], v[10:11]
	v_pk_add_f32 v[14:15], v[14:15], v[8:9]
	v_mov_b32_e32 v8, v122
	v_mov_b32_e32 v9, v123
	v_mov_b32_e32 v10, v124
	v_mov_b32_e32 v11, v125
	s_waitcnt lgkmcnt(0)
	v_pk_add_f32 v[16:17], v[16:17], v[10:11]
	v_pk_add_f32 v[14:15], v[14:15], v[8:9]
	v_mov_b32_e32 v8, v126
	v_mov_b32_e32 v9, v127
	v_mov_b32_e32 v10, v128
	v_mov_b32_e32 v11, v129
	s_waitcnt lgkmcnt(0)
	v_pk_add_f32 v[16:17], v[16:17], v[10:11]
	v_pk_add_f32 v[14:15], v[14:15], v[8:9]
	v_mov_b32_e32 v8, v172
	v_mov_b32_e32 v9, v173
	v_mov_b32_e32 v10, v174
	v_mov_b32_e32 v11, v175
	s_waitcnt lgkmcnt(0)
	v_pk_add_f32 v[16:17], v[16:17], v[10:11]
	v_pk_add_f32 v[24:25], v[14:15], v[8:9]
	v_mov_b32_e32 v8, v176
	v_mov_b32_e32 v9, v177
	v_mov_b32_e32 v10, v178
	v_mov_b32_e32 v11, v179
	v_mov_b32_e32 v34, v180
	v_mov_b32_e32 v35, v181
	v_mov_b32_e32 v36, v182
	v_mov_b32_e32 v37, v183
	s_waitcnt lgkmcnt(0)
	v_pk_add_f32 v[14:15], v[10:11], v[36:37]
	v_pk_add_f32 v[22:23], v[8:9], v[34:35]
	v_mov_b32_e32 v8, v184
	v_mov_b32_e32 v9, v185
	v_mov_b32_e32 v10, v186
	v_mov_b32_e32 v11, v187
	v_mov_b32_e32 v34, v188
	v_mov_b32_e32 v35, v189
	v_mov_b32_e32 v36, v190
	v_mov_b32_e32 v37, v191
	s_waitcnt lgkmcnt(1)
	v_pk_add_f32 v[14:15], v[14:15], v[10:11]
	v_pk_add_f32 v[22:23], v[22:23], v[8:9]
	v_mov_b32_e32 v8, v192
	v_mov_b32_e32 v9, v193
	v_mov_b32_e32 v10, v194
	v_mov_b32_e32 v11, v195
	s_waitcnt lgkmcnt(0)
	v_pk_add_f32 v[14:15], v[14:15], v[10:11]
	v_pk_add_f32 v[22:23], v[22:23], v[8:9]
	v_mov_b32_e32 v8, v196
	v_mov_b32_e32 v9, v197
	v_mov_b32_e32 v10, v198
	v_mov_b32_e32 v11, v199
	s_waitcnt lgkmcnt(0)
; __device__ __forceinline__ float bf1(bf16_t h) { return __uint_as_float((unsigned)h << 16); }
; __device__ __forceinline__ bf16_t f2bf(float f) { return (bf16_t)(pk2(f, 0.f) & 0xffffu); }
; __device__ __forceinline__ void sample_out_block(LAS unsigned char* lds, const bf16_t* A, const bf16_t* Bt, int K, bf16_t* xb, float* sspart, int blk, int tid) {
;     ...
;             for (int w = 1; w < 8; ++w) sum[nt] += part[(w * 8 + ra * 4 + nt) * 64 + lane];
;         }
;         float ss[4] = {0.f, 0.f, 0.f, 0.f};
; #pragma unroll
;         for (int j = 0; j < 4; ++j)
; #pragma unroll
;             for (int nt = 0; nt < 4; ++nt) {
;                 bf16_t* xp = xb + (size_t)(r0 + 16 * ra + 4 * g + j) * 2048 + 64 * cg + 16 * nt + l15;
;                 const bf16_t nv = f2bf(bf1(*xp) + sum[nt][j]);
;                 *xp = nv; const float r = bf1(nv); ss[j] += r * r;
;             }
; #pragma unroll
;         for (int j = 0; j < 4; ++j) {
;             float s = ss[j];
;             s += __shfl_xor(s, 1); s += __shfl_xor(s, 2); s += __shfl_xor(s, 4); s += __shfl_xor(s, 8);
;             if (l15 == 0) sspart[(size_t)(r0 + 16 * ra + 4 * g + j) * 32 + cg] = s;
	v_pk_add_f32 v[14:15], v[14:15], v[10:11]
	v_pk_add_f32 v[22:23], v[22:23], v[8:9]
	v_mov_b32_e32 v8, v200
	v_mov_b32_e32 v9, v201
	v_mov_b32_e32 v10, v202
	v_mov_b32_e32 v11, v203
	s_waitcnt lgkmcnt(0)
	v_pk_add_f32 v[14:15], v[14:15], v[10:11]
	v_pk_add_f32 v[22:23], v[22:23], v[8:9]
	v_mov_b32_e32 v8, v204
	v_mov_b32_e32 v9, v205
	v_mov_b32_e32 v10, v206
	v_mov_b32_e32 v11, v207
	s_waitcnt lgkmcnt(0)
	v_pk_add_f32 v[10:11], v[14:15], v[10:11]
	v_pk_add_f32 v[14:15], v[22:23], v[8:9]
	v_pk_add_f32 v[8:9], v[10:11], v[36:37]
	v_add_u32_e32 v10, s21, v31
	v_ashrrev_i32_e32 v11, 31, v10
	v_pk_add_f32 v[22:23], v[14:15], v[34:35]
	v_lshlrev_b64 v[14:15], 12, v[10:11]
	v_lshl_add_u64 v[14:15], v[28:29], 0, v[14:15]
	s_waitcnt vmcnt(0)
	v_mov_b32_e32 v0, v146
	v_lshlrev_b32_e32 v0, 16, v0
	v_add_f32_e32 v0, v20, v0
	v_cvt_pk_bf16_f32 v0, v0, s0
	global_store_short v[14:15], v0, off
	v_lshlrev_b32_e32 v20, 16, v0
	v_mov_b32_e32 v0, v147
	v_lshlrev_b32_e32 v0, 16, v0
	v_add_f32_e32 v0, v26, v0
	v_cvt_pk_bf16_f32 v0, v0, s0
	global_store_short v[14:15], v0, off offset:32
	v_lshlrev_b32_e32 v0, 16, v0
	v_mul_f32_e32 v0, v0, v0
	v_fmac_f32_e32 v0, v20, v20
	v_mov_b32_e32 v20, v148
	v_lshlrev_b32_e32 v20, 16, v20
	v_add_f32_e32 v20, v24, v20
	v_cvt_pk_bf16_f32 v20, v20, s0
	global_store_short v[14:15], v20, off offset:64
	v_lshlrev_b32_e32 v20, 16, v20
	v_fmac_f32_e32 v0, v20, v20
	v_mov_b32_e32 v20, v149
	v_lshlrev_b32_e32 v20, 16, v20
	v_add_f32_e32 v20, v22, v20
	v_cvt_pk_bf16_f32 v20, v20, s0
	global_store_short v[14:15], v20, off offset:96
	v_lshlrev_b32_e32 v14, 16, v20
	v_fmac_f32_e32 v0, v14, v14
	v_or_b32_e32 v14, 1, v10
	v_ashrrev_i32_e32 v15, 31, v14
	v_lshlrev_b64 v[34:35], 12, v[14:15]
	v_lshl_add_u64 v[36:37], v[28:29], 0, v[34:35]
	v_mov_b32_e32 v20, v150
	v_lshlrev_b32_e32 v20, 16, v20
	v_add_f32_e32 v20, v21, v20
	v_cvt_pk_bf16_f32 v26, v20, s0
	v_mov_b32_e32 v20, v151
	v_lshlrev_b32_e32 v20, 16, v20
	v_add_f32_e32 v20, v27, v20
	v_cvt_pk_bf16_f32 v27, v20, s0
	v_mov_b32_e32 v20, v152
	v_lshlrev_b32_e32 v20, 16, v20
	v_add_f32_e32 v20, v25, v20
	v_cvt_pk_bf16_f32 v34, v20, s0
	v_mov_b32_e32 v20, v153
	v_lshlrev_b32_e32 v20, 16, v20
	v_add_f32_e32 v20, v23, v20
	v_cvt_pk_bf16_f32 v35, v20, s0
	v_or_b32_e32 v20, 2, v10
	v_ashrrev_i32_e32 v21, 31, v20
	v_lshlrev_b64 v[22:23], 12, v[20:21]
	v_lshl_add_u64 v[22:23], v[28:29], 0, v[22:23]
	v_mov_b32_e32 v24, v154
	v_lshlrev_b32_e32 v24, 16, v24
	v_add_f32_e32 v12, v12, v24
	v_mov_b32_e32 v24, v155
	v_cvt_pk_bf16_f32 v12, v12, s0
	global_store_short v[22:23], v12, off
	global_store_short v[36:37], v26, off
	global_store_short v[36:37], v27, off offset:32
	global_store_short v[36:37], v34, off offset:64
	global_store_short v[36:37], v35, off offset:96
	v_xor_b32_e32 v36, 8, v215
	s_waitcnt vmcnt(5)
	v_lshlrev_b32_e32 v24, 16, v24
	v_add_f32_e32 v18, v18, v24
	v_mov_b32_e32 v24, v156
	v_cvt_pk_bf16_f32 v18, v18, s0
	global_store_short v[22:23], v18, off offset:32
	s_waitcnt vmcnt(1)
	v_lshlrev_b32_e32 v24, 16, v24
	v_add_f32_e32 v16, v16, v24
	v_mov_b32_e32 v24, v157
	v_cvt_pk_bf16_f32 v16, v16, s0
	global_store_short v[22:23], v16, off offset:64
	s_waitcnt vmcnt(1)
	v_lshlrev_b32_e32 v24, 16, v24
	v_add_f32_e32 v8, v8, v24
	v_cvt_pk_bf16_f32 v8, v8, s0
	global_store_short v[22:23], v8, off offset:96
	v_or_b32_e32 v22, 3, v10
	v_ashrrev_i32_e32 v23, 31, v22
	v_lshlrev_b64 v[24:25], 12, v[22:23]
	v_lshl_add_u64 v[24:25], v[28:29], 0, v[24:25]
	v_mov_b32_e32 v28, v158
	v_lshlrev_b32_e32 v28, 16, v28
	v_add_f32_e32 v13, v13, v28
	v_mov_b32_e32 v28, v159
	v_cvt_pk_bf16_f32 v13, v13, s0
	global_store_short v[24:25], v13, off
	s_waitcnt vmcnt(1)
	v_lshlrev_b32_e32 v28, 16, v28
	v_add_f32_e32 v19, v19, v28
	v_mov_b32_e32 v28, v160
	v_cvt_pk_bf16_f32 v19, v19, s0
	global_store_short v[24:25], v19, off offset:32
	s_waitcnt vmcnt(1)
	v_lshlrev_b32_e32 v28, 16, v28
	v_add_f32_e32 v17, v17, v28
	v_mov_b32_e32 v28, v161
	v_cvt_pk_bf16_f32 v17, v17, s0
	global_store_short v[24:25], v17, off offset:64
	s_waitcnt vmcnt(1)
	v_lshlrev_b32_e32 v28, 16, v28
	v_add_f32_e32 v9, v9, v28
	v_cvt_pk_bf16_f32 v9, v9, s0
	global_store_short v[24:25], v9, off offset:96
	v_and_b32_e32 v25, 64, v215
	v_xor_b32_e32 v24, 1, v215
	v_add_u32_e32 v29, 64, v25
	v_cmp_lt_i32_e32 vcc, v24, v29
	v_xor_b32_e32 v25, 2, v215
	v_xor_b32_e32 v28, 4, v215
	v_cndmask_b32_e32 v24, v215, v24, vcc
	v_cmp_lt_i32_e32 vcc, v25, v29
	v_lshlrev_b32_e32 v24, 2, v24
	s_nop 0
	v_cndmask_b32_e32 v25, v215, v25, vcc
	v_cmp_lt_i32_e32 vcc, v28, v29
	v_lshlrev_b32_e32 v25, 2, v25
	s_nop 0
	v_cndmask_b32_e32 v28, v215, v28, vcc
	v_cmp_lt_i32_e32 vcc, v36, v29
	v_lshlrev_b32_e32 v28, 2, v28
	s_nop 0
	v_cndmask_b32_e32 v29, v215, v36, vcc
	ds_bpermute_b32 v36, v24, v0
	v_lshlrev_b32_e32 v29, 2, v29
	s_waitcnt lgkmcnt(0)
	v_add_f32_e32 v0, v0, v36
	ds_bpermute_b32 v36, v25, v0
	s_waitcnt lgkmcnt(0)
	v_add_f32_e32 v0, v0, v36
	ds_bpermute_b32 v36, v28, v0
	s_waitcnt lgkmcnt(0)
	v_add_f32_e32 v0, v0, v36
	ds_bpermute_b32 v36, v29, v0
	s_and_saveexec_b64 s[20:21], s[6:7]
	s_cbranch_execz .LBB0_1168
	v_lshlrev_b64 v[10:11], 7, v[10:11]
	v_lshl_add_u64 v[10:11], s[10:11], 0, v[10:11]
	s_waitcnt lgkmcnt(0)
	v_add_f32_e32 v0, v0, v36
	global_store_dword v[10:11], v0, off

; #define LAS __attribute__((address_space(3)))
; __device__ __forceinline__ void sample_out_block(LAS unsigned char* lds, const bf16_t* A, const bf16_t* Bt, int K, bf16_t* xb, float* sspart, int blk, int tid) {
;     const int wave = tid >> 6, lane = tid & 63, l15 = lane & 15, g = lane >> 4;
;     const int rt = blk >> 5, cg = blk & 31, r0 = T_P + 32 * rt;
;     const int kq = K >> 3;
;     f32x4 acc[2][4];
; #pragma unroll
;     for (int ra = 0; ra < 2; ++ra)
; #pragma unroll
;         for (int nt = 0; nt < 4; ++nt) acc[ra][nt] = (f32x4){0.f, 0.f, 0.f, 0.f};
;     {
;         const bf16_t* ap = A + (size_t)(r0 + l15) * K + wave * kq + 8 * g;
;         const bf16_t* bp = Bt + (size_t)(64 * cg + l15) * K + wave * kq + 8 * g;
;         bf16x8 af[2][2], bf[2][4], afn[2][2], bfn[2][4];
; #pragma unroll
;         for (int s = 0; s < 2; ++s) {
; #pragma unroll
;             for (int ra = 0; ra < 2; ++ra) af[s][ra] = *(const bf16x8*)(ap + (size_t)(16 * ra) * K + 32 * s);
; #pragma unroll
;             for (int nt = 0; nt < 4; ++nt) bf[s][nt] = *(const bf16x8*)(bp + (size_t)(16 * nt) * K + 32 * s);
;         }
;         for (int k0 = 0; k0 < kq; k0 += 64) {
;             const int k1 = (k0 + 64 < kq) ? k0 + 64 : k0;
; #pragma unroll
;             for (int s = 0; s < 2; ++s) {
; #pragma unroll
;                 for (int ra = 0; ra < 2; ++ra) afn[s][ra] = *(const bf16x8*)(ap + (size_t)(16 * ra) * K + k1 + 32 * s);
; #pragma unroll
;                 for (int nt = 0; nt < 4; ++nt) bfn[s][nt] = *(const bf16x8*)(bp + (size_t)(16 * nt) * K + k1 + 32 * s);
;             }
; #pragma unroll
;             for (int s = 0; s < 2; ++s)
; #pragma unroll
;                 for (int ra = 0; ra < 2; ++ra)
; #pragma unroll
;                     for (int nt = 0; nt < 4; ++nt) acc[ra][nt] = MFMA16(af[s][ra], bf[s][nt], acc[ra][nt]);
; #pragma unroll
;             for (int s = 0; s < 2; ++s) {
; #pragma unroll
;                 for (int ra = 0; ra < 2; ++ra) af[s][ra] = afn[s][ra];
; #pragma unroll
;                 for (int nt = 0; nt < 4; ++nt) bf[s][nt] = bfn[s][nt];
;             }
;         }
;     }
;     LAS f32x4* part = (LAS f32x4*)lds;
; #pragma unroll
;     for (int ra = 0; ra < 2; ++ra)
; #pragma unroll
;         for (int nt = 0; nt < 4; ++nt) part[(wave * 8 + ra * 4 + nt) * 64 + lane] = acc[ra][nt];
;     __syncthreads();
.LBB0_1463:
	s_and_b32 s19, s26, 0xffffffe0
	s_addk_i32 s19, 0x2000
	s_and_b32 s18, s26, 31
	v_or_b32_e32 v8, s19, v30
	v_ashrrev_i32_e32 v9, 31, v8
	s_lshl_b32 s20, s18, 6
	v_lshlrev_b64 v[8:9], 10, v[8:9]
	v_or_b32_e32 v0, s20, v30
	v_lshl_add_u64 v[28:29], v[2:3], 0, v[8:9]
	v_lshlrev_b32_e32 v0, 10, v0
	v_lshl_add_u64 v[42:43], v[4:5], 0, v[0:1]
	v_add_co_u32_e32 v66, vcc, 0x4000, v28
	s_mov_b64 s[8:9], vcc
	v_add_co_u32_e32 v24, vcc, 0x4000, v42
	v_readfirstlane_b32 s36, v139
	s_lshr_b32 s36, s36, 6
	s_and_b32 s37, s26, 0xffffffe0
	s_addk_i32 s37, 0x2000
	s_and_b32 s38, s26, 31
	s_lshl_b32 s38, s38, 6
	s_lshl_b32 s39, s37, 10
	s_mul_i32 s40, s36, 0x80
	s_add_u32 s42, s16, s39
	s_addc_u32 s43, s17, 0
	s_add_u32 s42, s42, s40
	s_addc_u32 s43, s43, 0
	s_lshl_b32 s41, s24, 1
	s_lshl_b32 s39, s38, 10
	s_add_u32 s44, s22, s41
	s_addc_u32 s45, s23, 0
	s_add_u32 s44, s44, s39
	s_addc_u32 s45, s45, 0
	s_add_u32 s44, s44, s40
	s_addc_u32 s45, s45, 0
	v_lshrrev_b32_e32 v227, 3, v215
	v_and_b32_e32 v228, 7, v215
	v_lshlrev_b32_e32 v198, 10, v227
	v_lshl_add_u32 v198, v228, 4, v198
	v_add_u32_e32 v199, 0x2000, v198
	v_add_u32_e32 v200, 0x4000, v198
	v_add_u32_e32 v201, 0x6000, v198
	v_add_u32_e32 v202, 0x8000, v198
	v_add_u32_e32 v203, 0xa000, v198
	v_add_u32_e32 v204, 0xc000, v198
	v_add_u32_e32 v205, 0xe000, v198
	s_lshl_b32 s46, s36, 13
	s_mul_i32 s47, s36, 0x1800
	s_add_i32 s47, s47, 0x10000
	v_mul_u32_u24_e32 v206, 0x90, v227
	v_lshl_add_u32 v206, v228, 4, v206
	v_add_u32_e32 v207, s47, v206
	v_add_u32_e32 v206, s46, v206
	v_and_b32_e32 v227, 15, v215
	v_lshrrev_b32_e32 v228, 4, v215
	v_mul_u32_u24_e32 v208, 0x90, v227
	v_lshl_add_u32 v208, v228, 4, v208
	v_add_u32_e32 v209, s47, v208
	v_add_u32_e32 v208, s46, v208
	v_add_u32_e32 v226, 0x1b00, v208
	v_subrev_u32_e32 v228, 0x480, v209
	v_cmp_gt_u32_e32 vcc, 8, v227
	v_cndmask_b32_e32 v226, v228, v226, vcc
	global_load_dwordx4 v[34:37], v198, s[42:43]
	global_load_dwordx4 v[38:41], v199, s[42:43]
	global_load_dwordx4 v[42:45], v200, s[42:43]
	global_load_dwordx4 v[46:49], v201, s[42:43]
	global_load_dwordx4 v[50:53], v198, s[44:45]
	global_load_dwordx4 v[54:57], v199, s[44:45]
	global_load_dwordx4 v[58:61], v200, s[44:45]
	global_load_dwordx4 v[62:65], v201, s[44:45]
	global_load_dwordx4 v[66:69], v202, s[44:45]
	global_load_dwordx4 v[70:73], v203, s[44:45]
	global_load_dwordx4 v[74:77], v204, s[44:45]
	global_load_dwordx4 v[78:81], v205, s[44:45]
	s_waitcnt vmcnt(0)
	ds_write_b128 v206, v[34:37]
	ds_write_b128 v206, v[38:41] offset:1152
	ds_write_b128 v206, v[42:45] offset:2304
	ds_write_b128 v206, v[46:49] offset:3456
	ds_write_b128 v206, v[50:53] offset:4608
	ds_write_b128 v206, v[54:57] offset:5760
	ds_write_b128 v206, v[58:61] offset:6912
	ds_write_b128 v207, v[62:65]
	ds_write_b128 v207, v[66:69] offset:1152
	ds_write_b128 v207, v[70:73] offset:2304
	ds_write_b128 v207, v[74:77] offset:3456
	ds_write_b128 v207, v[78:81] offset:4608
	ds_read_b128 v[146:149], v208 offset:0
	ds_read_b128 v[150:153], v208 offset:2304
	ds_read_b128 v[154:157], v208 offset:4608
	ds_read_b128 v[158:161], v226
	ds_read_b128 v[162:165], v209 offset:1152
	ds_read_b128 v[166:169], v209 offset:3456
	ds_read_b128 v[170:173], v208 offset:64
	ds_read_b128 v[174:177], v208 offset:2368
	ds_read_b128 v[178:181], v208 offset:4672
	ds_read_b128 v[182:185], v226 offset:64
	ds_read_b128 v[186:189], v209 offset:1216
	ds_read_b128 v[190:193], v209 offset:3520
	s_waitcnt lgkmcnt(6)
	v_mfma_f32_16x16x32_bf16 v[8:11], v[146:149], v[154:157], 0
	v_mfma_f32_16x16x32_bf16 v[12:15], v[146:149], v[158:161], 0
	v_mfma_f32_16x16x32_bf16 v[16:19], v[146:149], v[162:165], 0
	v_mfma_f32_16x16x32_bf16 v[20:23], v[146:149], v[166:169], 0
	v_mfma_f32_16x16x32_bf16 v[24:27], v[150:153], v[154:157], 0
	v_mfma_f32_16x16x32_bf16 v[130:133], v[150:153], v[158:161], 0
	v_mfma_f32_16x16x32_bf16 v[134:137], v[150:153], v[162:165], 0
	v_mfma_f32_16x16x32_bf16 v[194:197], v[150:153], v[166:169], 0
	s_waitcnt lgkmcnt(0)
	v_mfma_f32_16x16x32_bf16 v[8:11], v[170:173], v[178:181], v[8:11]
	v_mfma_f32_16x16x32_bf16 v[12:15], v[170:173], v[182:185], v[12:15]
	v_mfma_f32_16x16x32_bf16 v[16:19], v[170:173], v[186:189], v[16:19]
	v_mfma_f32_16x16x32_bf16 v[20:23], v[170:173], v[190:193], v[20:23]
	v_mfma_f32_16x16x32_bf16 v[24:27], v[174:177], v[178:181], v[24:27]
	v_mfma_f32_16x16x32_bf16 v[130:133], v[174:177], v[182:185], v[130:133]
	v_mfma_f32_16x16x32_bf16 v[134:137], v[174:177], v[186:189], v[134:137]
	v_mfma_f32_16x16x32_bf16 v[194:197], v[174:177], v[190:193], v[194:197]
	s_nop 7
	s_nop 7
	ds_write_b128 v32, v[8:11]
	ds_write_b128 v32, v[12:15] offset:1024
	ds_write_b128 v32, v[16:19] offset:2048
	ds_write_b128 v32, v[20:23] offset:3072
	ds_write_b128 v32, v[24:27] offset:4096
	ds_write_b128 v32, v[130:133] offset:5120
	ds_write_b128 v32, v[134:137] offset:6144
	ds_write_b128 v32, v[194:197] offset:7168
	s_waitcnt lgkmcnt(0)
	s_barrier
	s_and_saveexec_b64 s[8:9], s[4:5]
	s_cbranch_execz .LBB0_1462
; __device__ __forceinline__ void sample_out_block(LAS unsigned char* lds, const bf16_t* A, const bf16_t* Bt, int K, bf16_t* xb, float* sspart, int blk, int tid) {
;     ...
;         const int ra = wave;
;         f32x4 sum[4];
; #pragma unroll
;         for (int nt = 0; nt < 4; ++nt) {
;             sum[nt] = part[(0 * 8 + ra * 4 + nt) * 64 + lane];
; #pragma unroll
;             for (int w = 1; w < 8; ++w) sum[nt] += part[(w * 8 + ra * 4 + nt) * 64 + lane];
;         }
	v_add_u32_e32 v170, s19, v31
	v_lshlrev_b32_e32 v170, 12, v170
	s_lshl_b32 s36, s20, 1
	v_add_u32_e32 v170, s36, v170
	v_mov_b32_e32 v171, 0
	s_mov_b64 s[38:39], 0x1000
	v_lshl_add_u64 v[162:163], v[6:7], 0, v[170:171]
	v_lshl_add_u64 v[164:165], v[162:163], 0, s[38:39]
	v_lshl_add_u64 v[166:167], v[164:165], 0, s[38:39]
	v_lshl_add_u64 v[168:169], v[166:167], 0, s[38:39]
	global_load_ushort v146, v[162:163], off
	global_load_ushort v147, v[162:163], off offset:32
	global_load_ushort v148, v[162:163], off offset:64
	global_load_ushort v149, v[162:163], off offset:96
	global_load_ushort v150, v[164:165], off
	global_load_ushort v151, v[164:165], off offset:32
	global_load_ushort v152, v[164:165], off offset:64
	global_load_ushort v153, v[164:165], off offset:96
	global_load_ushort v154, v[166:167], off
	global_load_ushort v155, v[166:167], off offset:32
	global_load_ushort v156, v[166:167], off offset:64
	global_load_ushort v157, v[166:167], off offset:96
	global_load_ushort v158, v[168:169], off
	global_load_ushort v159, v[168:169], off offset:32
	global_load_ushort v160, v[168:169], off offset:64
	global_load_ushort v161, v[168:169], off offset:96
	ds_read_b128 v[38:41], v33
	ds_read_b128 v[42:45], v33 offset:8192
	ds_read_b128 v[46:49], v33 offset:16384
	ds_read_b128 v[50:53], v33 offset:24576
	ds_read_b128 v[54:57], v33 offset:32768
	ds_read_b128 v[58:61], v33 offset:40960
	ds_read_b128 v[62:65], v33 offset:49152
	ds_read_b128 v[66:69], v33 offset:57344
	ds_read_b128 v[70:73], v33 offset:1024
	ds_read_b128 v[74:77], v33 offset:9216
	ds_read_b128 v[78:81], v33 offset:17408
	ds_read_b128 v[82:85], v33 offset:25600
	ds_read_b128 v[86:89], v33 offset:33792
	ds_read_b128 v[90:93], v33 offset:41984
	ds_read_b128 v[94:97], v33 offset:50176
	ds_read_b128 v[98:101], v33 offset:58368
	ds_read_b128 v[102:105], v33 offset:2048
	ds_read_b128 v[106:109], v33 offset:10240
	ds_read_b128 v[110:113], v33 offset:18432
	ds_read_b128 v[114:117], v33 offset:26624
	ds_read_b128 v[118:121], v33 offset:34816
	ds_read_b128 v[122:125], v33 offset:43008
	ds_read_b128 v[126:129], v33 offset:51200
	ds_read_b128 v[172:175], v33 offset:59392
	ds_read_b128 v[176:179], v33 offset:3072
	ds_read_b128 v[180:183], v33 offset:11264
	ds_read_b128 v[184:187], v33 offset:19456
	ds_read_b128 v[188:191], v33 offset:60416
	ds_read_b128 v[192:195], v33 offset:27648
	ds_read_b128 v[196:199], v33 offset:35840
	ds_read_b128 v[200:203], v33 offset:44032
	ds_read_b128 v[204:207], v33 offset:52224
	s_waitcnt lgkmcnt(0)
	v_mov_b32_e32 v8, v38
	v_mov_b32_e32 v9, v39
	v_mov_b32_e32 v10, v40
	v_mov_b32_e32 v11, v41
	v_mov_b32_e32 v12, v42
	v_mov_b32_e32 v13, v43
	v_mov_b32_e32 v14, v44
	v_mov_b32_e32 v15, v45
	s_lshl_b32 s80, s20, 1
	v_lshl_add_u64 v[28:29], v[6:7], 0, s[80:81]
	s_lshl_b32 s18, s18, 2
	s_add_u32 s18, s14, s18
	s_waitcnt lgkmcnt(0)
	v_pk_add_f32 v[14:15], v[10:11], v[14:15]
	v_pk_add_f32 v[12:13], v[8:9], v[12:13]
	v_mov_b32_e32 v8, v46
	v_mov_b32_e32 v9, v47
	v_mov_b32_e32 v10, v48
	v_mov_b32_e32 v11, v49
	s_waitcnt lgkmcnt(0)
	v_pk_add_f32 v[14:15], v[14:15], v[10:11]
	v_pk_add_f32 v[12:13], v[12:13], v[8:9]
	v_mov_b32_e32 v8, v50
	v_mov_b32_e32 v9, v51
	v_mov_b32_e32 v10, v52
	v_mov_b32_e32 v11, v53
	s_waitcnt lgkmcnt(0)
	v_pk_add_f32 v[14:15], v[14:15], v[10:11]
	v_pk_add_f32 v[12:13], v[12:13], v[8:9]
	v_mov_b32_e32 v8, v54
	v_mov_b32_e32 v9, v55
	v_mov_b32_e32 v10, v56
	v_mov_b32_e32 v11, v57
	s_waitcnt lgkmcnt(0)
	v_pk_add_f32 v[14:15], v[14:15], v[10:11]
	v_pk_add_f32 v[12:13], v[12:13], v[8:9]
	v_mov_b32_e32 v8, v58
	v_mov_b32_e32 v9, v59
	v_mov_b32_e32 v10, v60
	v_mov_b32_e32 v11, v61
	s_waitcnt lgkmcnt(0)
	v_pk_add_f32 v[14:15], v[14:15], v[10:11]
	v_pk_add_f32 v[12:13], v[12:13], v[8:9]
	v_mov_b32_e32 v8, v62
	v_mov_b32_e32 v9, v63
	v_mov_b32_e32 v10, v64
	v_mov_b32_e32 v11, v65
	s_waitcnt lgkmcnt(0)
	v_pk_add_f32 v[14:15], v[14:15], v[10:11]
	v_pk_add_f32 v[16:17], v[12:13], v[8:9]
	v_mov_b32_e32 v8, v66
	v_mov_b32_e32 v9, v67
	v_mov_b32_e32 v10, v68
	v_mov_b32_e32 v11, v69
	s_waitcnt lgkmcnt(0)
	v_pk_add_f32 v[12:13], v[14:15], v[10:11]
	v_pk_add_f32 v[20:21], v[16:17], v[8:9]
	v_mov_b32_e32 v8, v70
	v_mov_b32_e32 v9, v71
	v_mov_b32_e32 v10, v72
	v_mov_b32_e32 v11, v73
	v_mov_b32_e32 v14, v74
	v_mov_b32_e32 v15, v75
	v_mov_b32_e32 v16, v76
	v_mov_b32_e32 v17, v77
	s_waitcnt lgkmcnt(0)
	v_pk_add_f32 v[16:17], v[10:11], v[16:17]
	v_pk_add_f32 v[14:15], v[8:9], v[14:15]
	v_mov_b32_e32 v8, v78
	v_mov_b32_e32 v9, v79
	v_mov_b32_e32 v10, v80
	v_mov_b32_e32 v11, v81
	s_waitcnt lgkmcnt(0)
	v_pk_add_f32 v[16:17], v[16:17], v[10:11]
	v_pk_add_f32 v[14:15], v[14:15], v[8:9]
	v_mov_b32_e32 v8, v82
	v_mov_b32_e32 v9, v83
	v_mov_b32_e32 v10, v84
	v_mov_b32_e32 v11, v85
	s_waitcnt lgkmcnt(0)
	v_pk_add_f32 v[16:17], v[16:17], v[10:11]
	v_pk_add_f32 v[14:15], v[14:15], v[8:9]
	v_mov_b32_e32 v8, v86
	v_mov_b32_e32 v9, v87
	v_mov_b32_e32 v10, v88
	v_mov_b32_e32 v11, v89
	s_waitcnt lgkmcnt(0)
	v_pk_add_f32 v[16:17], v[16:17], v[10:11]
	v_pk_add_f32 v[14:15], v[14:15], v[8:9]
	v_mov_b32_e32 v8, v90
	v_mov_b32_e32 v9, v91
	v_mov_b32_e32 v10, v92
	v_mov_b32_e32 v11, v93
	s_waitcnt lgkmcnt(0)
	v_pk_add_f32 v[16:17], v[16:17], v[10:11]
	v_pk_add_f32 v[14:15], v[14:15], v[8:9]
	v_mov_b32_e32 v8, v94
	v_mov_b32_e32 v9, v95
	v_mov_b32_e32 v10, v96
	v_mov_b32_e32 v11, v97
	s_waitcnt lgkmcnt(0)
	v_pk_add_f32 v[16:17], v[16:17], v[10:11]
	v_pk_add_f32 v[14:15], v[14:15], v[8:9]
	v_mov_b32_e32 v8, v98
	v_mov_b32_e32 v9, v99
	v_mov_b32_e32 v10, v100
	v_mov_b32_e32 v11, v101
	s_waitcnt lgkmcnt(0)
; __device__ __forceinline__ float bf1(bf16_t h) { return __uint_as_float((unsigned)h << 16); }
; __device__ __forceinline__ bf16_t f2bf(float f) { return (bf16_t)(pk2(f, 0.f) & 0xffffu); }
; __device__ __forceinline__ void sample_out_block(LAS unsigned char* lds, const bf16_t* A, const bf16_t* Bt, int K, bf16_t* xb, float* sspart, int blk, int tid) {
;     ...
;         for (int nt = 0; nt < 4; ++nt) {
;             sum[nt] = part[(0 * 8 + ra * 4 + nt) * 64 + lane];
; #pragma unroll
;             for (int w = 1; w < 8; ++w) sum[nt] += part[(w * 8 + ra * 4 + nt) * 64 + lane];
;         }
;         float ss[4] = {0.f, 0.f, 0.f, 0.f};
; #pragma unroll
;         for (int j = 0; j < 4; ++j)
; #pragma unroll
;             for (int nt = 0; nt < 4; ++nt) {
;                 bf16_t* xp = xb + (size_t)(r0 + 16 * ra + 4 * g + j) * 2048 + 64 * cg + 16 * nt + l15;
;                 const bf16_t nv = f2bf(bf1(*xp) + sum[nt][j]);
	v_pk_add_f32 v[18:19], v[16:17], v[10:11]
	v_pk_add_f32 v[26:27], v[14:15], v[8:9]
	v_mov_b32_e32 v8, v102
	v_mov_b32_e32 v9, v103
	v_mov_b32_e32 v10, v104
	v_mov_b32_e32 v11, v105
	v_mov_b32_e32 v14, v106
	v_mov_b32_e32 v15, v107
	v_mov_b32_e32 v16, v108
	v_mov_b32_e32 v17, v109
	s_waitcnt lgkmcnt(0)
	v_pk_add_f32 v[16:17], v[10:11], v[16:17]
	v_pk_add_f32 v[14:15], v[8:9], v[14:15]
	v_mov_b32_e32 v8, v110
	v_mov_b32_e32 v9, v111
	v_mov_b32_e32 v10, v112
	v_mov_b32_e32 v11, v113
	s_waitcnt lgkmcnt(0)
	v_pk_add_f32 v[16:17], v[16:17], v[10:11]
	v_pk_add_f32 v[14:15], v[14:15], v[8:9]
	v_mov_b32_e32 v8, v114
	v_mov_b32_e32 v9, v115
	v_mov_b32_e32 v10, v116
	v_mov_b32_e32 v11, v117
	s_waitcnt lgkmcnt(0)
	v_pk_add_f32 v[16:17], v[16:17], v[10:11]
	v_pk_add_f32 v[14:15], v[14:15], v[8:9]
	v_mov_b32_e32 v8, v118
	v_mov_b32_e32 v9, v119
	v_mov_b32_e32 v10, v120
	v_mov_b32_e32 v11, v121
	s_waitcnt lgkmcnt(0)
	v_pk_add_f32 v[16:17], v[16:17], v[10:11]
	v_pk_add_f32 v[14:15], v[14:15], v[8:9]
	v_mov_b32_e32 v8, v122
	v_mov_b32_e32 v9, v123
	v_mov_b32_e32 v10, v124
	v_mov_b32_e32 v11, v125
	s_waitcnt lgkmcnt(0)
	v_pk_add_f32 v[16:17], v[16:17], v[10:11]
	v_pk_add_f32 v[14:15], v[14:15], v[8:9]
	v_mov_b32_e32 v8, v126
	v_mov_b32_e32 v9, v127
	v_mov_b32_e32 v10, v128
	v_mov_b32_e32 v11, v129
	s_waitcnt lgkmcnt(0)
	v_pk_add_f32 v[16:17], v[16:17], v[10:11]
	v_pk_add_f32 v[14:15], v[14:15], v[8:9]
	v_mov_b32_e32 v8, v172
	v_mov_b32_e32 v9, v173
	v_mov_b32_e32 v10, v174
	v_mov_b32_e32 v11, v175
	s_waitcnt lgkmcnt(0)
	v_pk_add_f32 v[16:17], v[16:17], v[10:11]
	v_pk_add_f32 v[24:25], v[14:15], v[8:9]
	v_mov_b32_e32 v8, v176
	v_mov_b32_e32 v9, v177
	v_mov_b32_e32 v10, v178
	v_mov_b32_e32 v11, v179
	v_mov_b32_e32 v34, v180
	v_mov_b32_e32 v35, v181
	v_mov_b32_e32 v36, v182
	v_mov_b32_e32 v37, v183
	s_waitcnt lgkmcnt(0)
	v_pk_add_f32 v[14:15], v[10:11], v[36:37]
	v_pk_add_f32 v[22:23], v[8:9], v[34:35]
	v_mov_b32_e32 v8, v184
	v_mov_b32_e32 v9, v185
	v_mov_b32_e32 v10, v186
	v_mov_b32_e32 v11, v187
	v_mov_b32_e32 v34, v188
	v_mov_b32_e32 v35, v189
	v_mov_b32_e32 v36, v190
	v_mov_b32_e32 v37, v191
	s_waitcnt lgkmcnt(1)
	v_pk_add_f32 v[14:15], v[14:15], v[10:11]
	v_pk_add_f32 v[22:23], v[22:23], v[8:9]
	v_mov_b32_e32 v8, v192
	v_mov_b32_e32 v9, v193
	v_mov_b32_e32 v10, v194
	v_mov_b32_e32 v11, v195
	s_waitcnt lgkmcnt(0)
	v_pk_add_f32 v[14:15], v[14:15], v[10:11]
	v_pk_add_f32 v[22:23], v[22:23], v[8:9]
	v_mov_b32_e32 v8, v196
	v_mov_b32_e32 v9, v197
	v_mov_b32_e32 v10, v198
	v_mov_b32_e32 v11, v199
	s_waitcnt lgkmcnt(0)
	v_pk_add_f32 v[14:15], v[14:15], v[10:11]
	v_pk_add_f32 v[22:23], v[22:23], v[8:9]
	v_mov_b32_e32 v8, v200
	v_mov_b32_e32 v9, v201
	v_mov_b32_e32 v10, v202
	v_mov_b32_e32 v11, v203
	s_waitcnt lgkmcnt(0)
	v_pk_add_f32 v[14:15], v[14:15], v[10:11]
	v_pk_add_f32 v[22:23], v[22:23], v[8:9]
	v_mov_b32_e32 v8, v204
	v_mov_b32_e32 v9, v205
	v_mov_b32_e32 v10, v206
	v_mov_b32_e32 v11, v207
	s_waitcnt lgkmcnt(0)
	v_pk_add_f32 v[10:11], v[14:15], v[10:11]
	v_pk_add_f32 v[14:15], v[22:23], v[8:9]
	v_pk_add_f32 v[8:9], v[10:11], v[36:37]
	v_add_u32_e32 v10, s19, v31
	v_ashrrev_i32_e32 v11, 31, v10
	v_pk_add_f32 v[22:23], v[14:15], v[34:35]
	v_lshlrev_b64 v[14:15], 12, v[10:11]
	v_lshl_add_u64 v[14:15], v[28:29], 0, v[14:15]
	s_waitcnt vmcnt(0)
	v_mov_b32_e32 v0, v146
	s_addc_u32 s19, s15, 0
	s_waitcnt vmcnt(0)
; __device__ __forceinline__ float bf1(bf16_t h) { return __uint_as_float((unsigned)h << 16); }
; __device__ __forceinline__ bf16_t f2bf(float f) { return (bf16_t)(pk2(f, 0.f) & 0xffffu); }
; __device__ __forceinline__ void sample_out_block(LAS unsigned char* lds, const bf16_t* A, const bf16_t* Bt, int K, bf16_t* xb, float* sspart, int blk, int tid) {
;     ...
;                 bf16_t* xp = xb + (size_t)(r0 + 16 * ra + 4 * g + j) * 2048 + 64 * cg + 16 * nt + l15;
;                 const bf16_t nv = f2bf(bf1(*xp) + sum[nt][j]);
;                 *xp = nv; const float r = bf1(nv); ss[j] += r * r;
;             }
; #pragma unroll
;         for (int j = 0; j < 4; ++j) {
;             float s = ss[j];
;             s += __shfl_xor(s, 1); s += __shfl_xor(s, 2); s += __shfl_xor(s, 4); s += __shfl_xor(s, 8);
;             if (l15 == 0) sspart[(size_t)(r0 + 16 * ra + 4 * g + j) * 32 + cg] = s;
	v_lshlrev_b32_e32 v0, 16, v0
	v_add_f32_e32 v0, v20, v0
	v_cvt_pk_bf16_f32 v0, v0, s0
	global_store_short v[14:15], v0, off
	v_lshlrev_b32_e32 v20, 16, v0
	v_mov_b32_e32 v0, v147
	v_lshlrev_b32_e32 v0, 16, v0
	v_add_f32_e32 v0, v26, v0
	v_cvt_pk_bf16_f32 v0, v0, s0
	global_store_short v[14:15], v0, off offset:32
	v_lshlrev_b32_e32 v0, 16, v0
	v_mul_f32_e32 v0, v0, v0
	v_fmac_f32_e32 v0, v20, v20
	v_mov_b32_e32 v20, v148
	v_lshlrev_b32_e32 v20, 16, v20
	v_add_f32_e32 v20, v24, v20
	v_cvt_pk_bf16_f32 v20, v20, s0
	global_store_short v[14:15], v20, off offset:64
	v_lshlrev_b32_e32 v20, 16, v20
	v_fmac_f32_e32 v0, v20, v20
	v_mov_b32_e32 v20, v149
	v_lshlrev_b32_e32 v20, 16, v20
	v_add_f32_e32 v20, v22, v20
	v_cvt_pk_bf16_f32 v20, v20, s0
	global_store_short v[14:15], v20, off offset:96
	v_lshlrev_b32_e32 v14, 16, v20
	v_fmac_f32_e32 v0, v14, v14
	v_or_b32_e32 v14, 1, v10
	v_ashrrev_i32_e32 v15, 31, v14
	v_lshlrev_b64 v[34:35], 12, v[14:15]
	v_lshl_add_u64 v[36:37], v[28:29], 0, v[34:35]
	v_mov_b32_e32 v20, v150
	v_lshlrev_b32_e32 v20, 16, v20
	v_add_f32_e32 v20, v21, v20
	v_cvt_pk_bf16_f32 v26, v20, s0
	v_mov_b32_e32 v20, v151
	v_lshlrev_b32_e32 v20, 16, v20
	v_add_f32_e32 v20, v27, v20
	v_cvt_pk_bf16_f32 v27, v20, s0
	v_mov_b32_e32 v20, v152
	v_lshlrev_b32_e32 v20, 16, v20
	v_add_f32_e32 v20, v25, v20
	v_cvt_pk_bf16_f32 v34, v20, s0
	v_mov_b32_e32 v20, v153
	v_lshlrev_b32_e32 v20, 16, v20
	v_add_f32_e32 v20, v23, v20
	v_cvt_pk_bf16_f32 v35, v20, s0
	v_or_b32_e32 v20, 2, v10
	v_ashrrev_i32_e32 v21, 31, v20
	v_lshlrev_b64 v[22:23], 12, v[20:21]
	v_lshl_add_u64 v[22:23], v[28:29], 0, v[22:23]
	v_mov_b32_e32 v24, v154
	v_lshlrev_b32_e32 v24, 16, v24
	v_add_f32_e32 v12, v12, v24
	v_mov_b32_e32 v24, v155
	v_cvt_pk_bf16_f32 v12, v12, s0
	global_store_short v[22:23], v12, off
	global_store_short v[36:37], v26, off
	global_store_short v[36:37], v27, off offset:32
	global_store_short v[36:37], v34, off offset:64
	global_store_short v[36:37], v35, off offset:96
	v_xor_b32_e32 v36, 8, v215
	s_waitcnt vmcnt(5)
	v_lshlrev_b32_e32 v24, 16, v24
	v_add_f32_e32 v18, v18, v24
	v_mov_b32_e32 v24, v156
	v_cvt_pk_bf16_f32 v18, v18, s0
	global_store_short v[22:23], v18, off offset:32
	s_waitcnt vmcnt(1)
	v_lshlrev_b32_e32 v24, 16, v24
	v_add_f32_e32 v16, v16, v24
	v_mov_b32_e32 v24, v157
	v_cvt_pk_bf16_f32 v16, v16, s0
	global_store_short v[22:23], v16, off offset:64
	s_waitcnt vmcnt(1)
	v_lshlrev_b32_e32 v24, 16, v24
	v_add_f32_e32 v8, v8, v24
	v_cvt_pk_bf16_f32 v8, v8, s0
	global_store_short v[22:23], v8, off offset:96
	v_or_b32_e32 v22, 3, v10
	v_ashrrev_i32_e32 v23, 31, v22
	v_lshlrev_b64 v[24:25], 12, v[22:23]
	v_lshl_add_u64 v[24:25], v[28:29], 0, v[24:25]
	v_mov_b32_e32 v28, v158
	v_lshlrev_b32_e32 v28, 16, v28
	v_add_f32_e32 v13, v13, v28
	v_mov_b32_e32 v28, v159
	v_cvt_pk_bf16_f32 v13, v13, s0
	global_store_short v[24:25], v13, off
	s_waitcnt vmcnt(1)
	v_lshlrev_b32_e32 v28, 16, v28
	v_add_f32_e32 v19, v19, v28
	v_mov_b32_e32 v28, v160
	v_cvt_pk_bf16_f32 v19, v19, s0
	global_store_short v[24:25], v19, off offset:32
	s_waitcnt vmcnt(1)
	v_lshlrev_b32_e32 v28, 16, v28
	v_add_f32_e32 v17, v17, v28
	v_mov_b32_e32 v28, v161
	v_cvt_pk_bf16_f32 v17, v17, s0
	global_store_short v[24:25], v17, off offset:64
	s_waitcnt vmcnt(1)
	v_lshlrev_b32_e32 v28, 16, v28
	v_add_f32_e32 v9, v9, v28
	v_cvt_pk_bf16_f32 v9, v9, s0
	global_store_short v[24:25], v9, off offset:96
	v_and_b32_e32 v25, 64, v215
	v_xor_b32_e32 v24, 1, v215
	v_add_u32_e32 v29, 64, v25
	v_cmp_lt_i32_e32 vcc, v24, v29
	v_xor_b32_e32 v25, 2, v215
	v_xor_b32_e32 v28, 4, v215
	v_cndmask_b32_e32 v24, v215, v24, vcc
	v_cmp_lt_i32_e32 vcc, v25, v29
	v_lshlrev_b32_e32 v24, 2, v24
	s_nop 0
	v_cndmask_b32_e32 v25, v215, v25, vcc
	v_cmp_lt_i32_e32 vcc, v28, v29
	v_lshlrev_b32_e32 v25, 2, v25
	s_nop 0
	v_cndmask_b32_e32 v28, v215, v28, vcc
	v_cmp_lt_i32_e32 vcc, v36, v29
	v_lshlrev_b32_e32 v28, 2, v28
	s_nop 0
	v_cndmask_b32_e32 v29, v215, v36, vcc
	ds_bpermute_b32 v36, v24, v0
	v_lshlrev_b32_e32 v29, 2, v29
	s_waitcnt lgkmcnt(0)
	v_add_f32_e32 v0, v0, v36
	ds_bpermute_b32 v36, v25, v0
	s_waitcnt lgkmcnt(0)
	v_add_f32_e32 v0, v0, v36
	ds_bpermute_b32 v36, v28, v0
	s_waitcnt lgkmcnt(0)
	v_add_f32_e32 v0, v0, v36
	ds_bpermute_b32 v36, v29, v0
	s_and_saveexec_b64 s[20:21], s[6:7]
	s_cbranch_execz .LBB0_1466
	v_lshlrev_b64 v[10:11], 7, v[10:11]
	v_lshl_add_u64 v[10:11], s[18:19], 0, v[10:11]
	s_waitcnt lgkmcnt(0)
	v_add_f32_e32 v0, v0, v36
	global_store_dword v[10:11], v0, off
